# combined: fin middle-variant counted vmcnt waits, dropped redundant epilogue vmcnt(0), trimmed setprio and post-barrier waits in GEMM loops
# speedup vs baseline: 1.0241x; 1.0070x over previous
; #define GAS __attribute__((address_space(1)))
; template <bool HIN_F32, bool LAST>
; __device__ __forceinline__ void fin_phase(const float* x, float* out, bf16_t* HI, unsigned char* LO, float* rs, const bf16_t* f, const float* ss, const float* gpost, float coef, int gw, int NGW, int rend, int lane) {
;     f32x4 gpv[4];
; #pragma unroll
;     for (int j = 0; j < 4; ++j) gpv[j] = *(const GAS f32x4*)(gpost + 512 * (j >> 1) + 8 * lane + 4 * (j & 1));
;     FinStage S[3];
;     fin_load<HIN_F32>(S[0], x, HI, LO, f, ss, gw, NGW, lane);
;     if (gw + 2 * NGW < rend) fin_load<HIN_F32>(S[1], x, HI, LO, f, ss, gw + 2 * NGW, NGW, lane);
;     for (int base = gw; base < rend; base += 6 * NGW) {
; #pragma unroll
;         for (int u = 0; u < 3; ++u) {
;             const int rowc = base + 2 * NGW * u, rowl = rowc + 4 * NGW;
;             if (rowl < rend) fin_load<HIN_F32>(S[(u + 2) % 3], x, HI, LO, f, ss, rowl, NGW, lane);
.LBB0_269:
	s_cmp_ge_i32 s2, s51
	s_cbranch_scc1 .LBB0_294
	s_mov_b32 s100, 0
	v_and_b32_e32 v82, 64, v191
	v_add_u32_e32 v82, 64, v82
	v_xor_b32_e32 v83, 1, v191
	v_cmp_lt_i32_e32 vcc, v83, v82
	s_lshl_b64 s[46:47], s[2:3], 2
	s_add_u32 s7, s46, 0x900000
	v_cndmask_b32_e32 v83, v191, v83, vcc
	v_lshlrev_b32_e32 v184, 2, v83
	v_xor_b32_e32 v83, 2, v191
	v_cmp_lt_i32_e32 vcc, v83, v82
	s_waitcnt vmcnt(1)
	v_mov_b64_e32 v[136:137], v[48:49]
	v_mov_b64_e32 v[132:133], v[40:41]
	v_cndmask_b32_e32 v83, v191, v83, vcc
	v_lshlrev_b32_e32 v185, 2, v83
	v_xor_b32_e32 v83, 4, v191
	v_cmp_lt_i32_e32 vcc, v83, v82
	v_mov_b64_e32 v[128:129], v[30:31]
	v_mov_b64_e32 v[112:113], v[22:23]
	v_cndmask_b32_e32 v83, v191, v83, vcc
	v_lshlrev_b32_e32 v195, 2, v83
	v_xor_b32_e32 v83, 8, v191
	v_cmp_lt_i32_e32 vcc, v83, v82
	v_mov_b64_e32 v[140:141], v[44:45]
	v_mov_b64_e32 v[144:145], v[36:37]
	v_cndmask_b32_e32 v83, v191, v83, vcc
	v_lshlrev_b32_e32 v196, 2, v83
	v_xor_b32_e32 v83, 16, v191
	v_cmp_lt_i32_e32 vcc, v83, v82
	v_mov_b64_e32 v[116:117], v[26:27]
	v_mov_b64_e32 v[120:121], v[18:19]
	v_cndmask_b32_e32 v83, v191, v83, vcc
	v_lshlrev_b32_e32 v197, 2, v83
	v_xor_b32_e32 v83, 32, v191
	v_cmp_lt_i32_e32 vcc, v83, v82
	v_cmp_eq_u32_e64 s[40:41], 0, v193
	s_addc_u32 s82, s47, 0
	v_cndmask_b32_e32 v82, v191, v83, vcc
	v_lshlrev_b32_e32 v198, 2, v82
	v_lshlrev_b32_e32 v82, 1, v177
	v_mov_b32_e32 v83, v32
	v_lshl_add_u64 v[156:157], s[62:63], 0, v[82:83]
	v_lshl_add_u64 v[158:159], s[68:69], 0, v[82:83]
	v_lshl_add_u64 v[160:161], s[44:45], 0, v[152:153]
	v_lshl_or_b32 v170, v193, 4, s8
	v_mov_b32_e32 v171, s9
	s_waitcnt vmcnt(0)
	v_mov_b32_e32 v208, v176
	v_mov_b32_e32 v205, v173
	v_mov_b64_e32 v[134:135], v[46:47]
	v_mov_b64_e32 v[130:131], v[38:39]
	v_mov_b64_e32 v[126:127], v[28:29]
	v_mov_b64_e32 v[110:111], v[20:21]
	v_mov_b32_e32 v209, v175
	v_mov_b32_e32 v207, v174
	v_mov_b32_e32 v206, v172
	v_mov_b32_e32 v204, v149
	v_mov_b64_e32 v[138:139], v[42:43]
	v_mov_b64_e32 v[142:143], v[34:35]
	v_mov_b64_e32 v[114:115], v[24:25]
	v_mov_b64_e32 v[118:119], v[16:17]
	s_mov_b32 s83, s2
	s_branch .LBB0_273

; #define GAS __attribute__((address_space(1)))
; __device__ __forceinline__ float bf_lo(unsigned w) { return __uint_as_float(w << 16); }
; template <bool HIN_F32>
; __device__ __forceinline__ void fin_load(FinStage& S, const float* x, const bf16_t* HI, const unsigned char* LO, const bf16_t* f, const float* ss, int row0, int NGW, int lane) {
;     ...
;     for (int t = 0; t < 2; ++t) { const int row = row0 + t * NGW;
; #pragma unroll
;         for (int j = 0; j < 2; ++j) { const int idx = 512 * j + 8 * lane;
;             if (HIN_F32) { S.v[t][j][0] = __builtin_nontemporal_load((const GAS f32x4*)(x + (size_t)row * DM + idx)); S.v[t][j][1] = __builtin_nontemporal_load((const GAS f32x4*)(x + (size_t)row * DM + idx + 4)); }
;             else { S.hw[t][j] = __builtin_nontemporal_load((const GAS u32x4*)(HI + (size_t)row * DM + idx)); S.lw[t][j] = __builtin_nontemporal_load((const GAS unsigned*)(LO + (size_t)row * (DM / 2) + (idx >> 1))); }
;             S.fw[t][j] = __builtin_nontemporal_load((const GAS u32x4*)(f + (size_t)row * DM + idx)); }
;         S.sp[t] = *(const GAS float*)(ss + (size_t)row * 16 + (lane & 15)); }
; }
; template <bool HIN_F32, bool LAST>
; __device__ __forceinline__ void fin_compute(FinStage& S, float* out, bf16_t* HI, unsigned char* LO, float* rs, const f32x4 (&gpv)[4], float coef, int row0, int NGW, int lane) {
; #pragma unroll
;     for (int t = 0; t < 2; ++t) { const int row = row0 + t * NGW; float s2 = 0.f;
;         float tot = S.sp[t];
; #pragma unroll
;         for (int o = 1; o < 16; o <<= 1) tot += __shfl_xor(tot, o);
;         const float r = coef * __builtin_amdgcn_rsqf(tot * (1.0f / DM) + RMS_EPS);
; #pragma unroll
;         for (int j = 0; j < 2; ++j) { const int idx = 512 * j + 8 * lane; float v[8];
;             const u32x4 fw = S.fw[t][j];
;             if (HIN_F32) {
; #pragma unroll
;                 for (int e = 0; e < 8; ++e) v[e] = S.v[t][j][e >> 2][e & 3];
;             } else { const u32x4 hw = S.hw[t][j]; const unsigned lw = S.lw[t][j];
; #pragma unroll
;                 for (int e = 0; e < 8; ++e) { const unsigned w = hw[e >> 1]; v[e] = lo_decode((e & 1) ? (w >> 16) : (w & 0xffffu), (int)(lw << (28 - 4 * e)) >> 28); } }
; #pragma unroll
;             for (int e = 0; e < 8; ++e) { const unsigned w = fw[e >> 1]; v[e] += ((e & 1) ? bf_hi(w) : bf_lo(w)) * r * gpv[2 * j + (e >> 2)][e & 3]; }
.LBB0_273:
	s_add_i32 s8, s73, s83
	s_cmp_lt_i32 s8, s51
	s_cselect_b64 s[76:77], -1, 0
	s_cmp_ge_i32 s8, s51
	s_cselect_b32 s100, 1, s100
	s_cbranch_scc1 .LBB0_275
	s_ashr_i32 s9, s8, 31
	s_lshl_b64 s[44:45], s[8:9], 9
	s_add_u32 s44, s0, s44
	s_addc_u32 s45, s50, s45
	s_lshl_b64 s[46:47], s[8:9], 11
	v_lshl_add_u64 v[86:87], v[156:157], 0, s[46:47]
	v_lshl_add_u64 v[82:83], s[44:45], 0, v[152:153]
	v_lshl_add_u64 v[88:89], v[158:159], 0, s[46:47]
	global_load_dword v199, v[82:83], off nt
	s_nop 0
	global_load_dwordx4 v[82:85], v[88:89], off nt
	global_load_dwordx4 v[94:97], v[86:87], off nt
	global_load_dwordx4 v[90:93], v[86:87], off offset:1024 nt
	v_lshl_add_u64 v[86:87], s[44:45], 0, v[154:155]
	s_lshl_b64 s[44:45], s[8:9], 6
	v_lshl_add_u64 v[98:99], v[150:151], 0, s[44:45]
	s_add_i32 s44, s85, s83
	s_ashr_i32 s45, s44, 31
	s_lshl_b64 s[46:47], s[44:45], 9
	s_add_u32 s46, s0, s46
	s_addc_u32 s47, s50, s47
	s_lshl_b64 s[48:49], s[44:45], 11
	global_load_dword v200, v[86:87], off nt
	global_load_dword v202, v[98:99], off
	s_nop 0
	global_load_dwordx4 v[86:89], v[88:89], off offset:1024 nt
	v_lshl_add_u64 v[102:103], v[156:157], 0, s[48:49]
	v_lshl_add_u64 v[98:99], s[46:47], 0, v[152:153]
	s_lshl_b64 s[44:45], s[44:45], 6
	v_lshl_add_u64 v[122:123], v[158:159], 0, s[48:49]
	global_load_dword v201, v[98:99], off nt
	s_nop 0
	global_load_dwordx4 v[98:101], v[122:123], off nt
	global_load_dwordx4 v[106:109], v[102:103], off nt
	s_nop 0
	global_load_dwordx4 v[102:105], v[102:103], off offset:1024 nt
	v_lshl_add_u64 v[124:125], s[46:47], 0, v[154:155]
	v_lshl_add_u64 v[210:211], v[150:151], 0, s[44:45]
	global_load_dword v203, v[124:125], off nt
	s_nop 0
	global_load_dword v210, v[210:211], off
	s_nop 0
	global_load_dwordx4 v[122:125], v[122:123], off offset:1024 nt
.LBB0_275:
	s_waitcnt vmcnt(48)
	s_cmp_eq_u32 s100, 0
	s_cbranch_scc1 .Lfin_mid_S_go
	s_waitcnt vmcnt(0)
.Lfin_mid_S_go:
	ds_bpermute_b32 v211, v184, v205
	v_lshlrev_b32_e32 v213, 24, v204
	v_and_b32_sdwa v213, sext(v213), s57 dst_sel:DWORD dst_unused:UNUSED_PAD src0_sel:WORD_1 src1_sel:DWORD
	s_mov_b32 s9, 0xaa00000
	s_waitcnt lgkmcnt(0)
	v_add_f32_e32 v211, v205, v211
	ds_bpermute_b32 v212, v185, v211
	s_waitcnt lgkmcnt(0)
	v_add_f32_e32 v211, v211, v212
	ds_bpermute_b32 v212, v195, v211
	s_waitcnt lgkmcnt(0)
	v_add_f32_e32 v211, v211, v212
	ds_bpermute_b32 v212, v196, v211
	s_waitcnt lgkmcnt(0)
	v_add_f32_e32 v211, v211, v212
	v_lshlrev_b32_e32 v212, 28, v204
	v_ashrrev_i32_e32 v212, 16, v212
	v_lshl_add_u32 v216, v118, 16, v212
	v_and_b32_e32 v212, 0xffff0000, v118
	v_add_u32_e32 v217, v212, v213
	v_lshlrev_b32_e32 v212, 20, v204
	v_and_b32_sdwa v212, sext(v212), s57 dst_sel:DWORD dst_unused:UNUSED_PAD src0_sel:WORD_1 src1_sel:DWORD
	v_lshl_add_u32 v218, v119, 16, v212
	v_and_b32_e32 v212, 0xffff0000, v119
	v_and_b32_sdwa v213, sext(v204), s57 dst_sel:DWORD dst_unused:UNUSED_PAD src0_sel:WORD_0 src1_sel:DWORD
	v_add_u32_e32 v219, v212, v213
	v_bfe_i32 v212, v204, 4, 16
	v_fmamk_f32 v211, v211, 0x3a800000, v188
	v_and_b32_e32 v212, 0xfffff000, v212
	v_bfe_i32 v213, v204, 8, 16
	v_rsq_f32_e32 v211, v211
	v_lshl_add_u32 v220, v120, 16, v212
	v_and_b32_e32 v212, 0xffff0000, v120
	v_and_b32_e32 v213, 0xfffff000, v213
	v_add_u32_e32 v221, v212, v213
	v_bfe_i32 v212, v204, 12, 16
	v_and_b32_e32 v212, 0xfffff000, v212
	v_lshl_add_u32 v222, v121, 16, v212
	v_and_b32_e32 v212, 0xffff0000, v121
	v_and_b32_sdwa v213, sext(v204), s57 dst_sel:DWORD dst_unused:UNUSED_PAD src0_sel:WORD_1 src1_sel:DWORD
	v_mul_f32_e32 v211, v33, v211
	v_add_u32_e32 v223, v212, v213
	v_lshlrev_b32_e32 v212, 16, v110
	v_mul_f32_e32 v212, v211, v212
	v_fmac_f32_e32 v216, v4, v212
	v_and_b32_e32 v212, 0xffff0000, v110
	v_mul_f32_e32 v212, v211, v212
	v_fmac_f32_e32 v217, v5, v212
	v_lshlrev_b32_e32 v212, 16, v111
	v_mul_f32_e32 v212, v211, v212
	v_fmac_f32_e32 v218, v6, v212
	v_and_b32_e32 v212, 0xffff0000, v111
	v_mul_f32_e32 v212, v211, v212
	v_fmac_f32_e32 v219, v7, v212
	v_lshlrev_b32_e32 v212, 16, v112
	v_mul_f32_e32 v212, v211, v212
	v_fmac_f32_e32 v220, v0, v212
	v_and_b32_e32 v212, 0xffff0000, v112
	v_mul_f32_e32 v212, v211, v212
	v_fmac_f32_e32 v221, v1, v212
	v_lshlrev_b32_e32 v212, 16, v113
	v_mul_f32_e32 v212, v211, v212
	v_fmac_f32_e32 v222, v2, v212
	v_and_b32_e32 v212, 0xffff0000, v113
	v_mul_f32_e32 v226, v217, v217
	v_mul_f32_e32 v212, v211, v212
	v_fmac_f32_e32 v226, v216, v216
	v_fmac_f32_e32 v223, v3, v212
	v_cvt_pk_bf16_f32 v212, v216, v217
	v_fmac_f32_e32 v226, v218, v218
	v_and_b32_e32 v225, 0xffff0000, v212
	v_cvt_pk_bf16_f32 v213, v218, v219
	v_lshlrev_b32_e32 v224, 16, v212
	v_sub_u32_e32 v225, v217, v225
	v_and_b32_e32 v217, 0xffff0000, v213
	v_fmac_f32_e32 v226, v219, v219
	v_cvt_pk_bf16_f32 v214, v220, v221
	v_sub_u32_e32 v224, v216, v224
	v_lshlrev_b32_e32 v216, 16, v213
	v_sub_u32_e32 v217, v219, v217
	v_fmac_f32_e32 v226, v220, v220
	v_and_b32_e32 v219, 0xffff0000, v214
	v_cvt_pk_bf16_f32 v215, v222, v223
	v_sub_u32_e32 v216, v218, v216
	v_sub_u32_e32 v219, v221, v219
	v_fmac_f32_e32 v226, v221, v221
	v_and_b32_e32 v221, 0xffff0000, v215
	v_add_u32_e32 v224, 0x800, v224
	v_add_u32_e32 v225, 0x800, v225
	v_add_u32_e32 v216, 0x800, v216
	v_lshlrev_b32_e32 v218, 16, v214
	v_sub_u32_e32 v221, v223, v221
	v_ashrrev_i32_e32 v224, 12, v224
	v_ashrrev_i32_e32 v225, 12, v225
	v_ashrrev_i32_e32 v216, 12, v216
	v_add_u32_e32 v217, 0x800, v217
	v_sub_u32_e32 v218, v220, v218
	v_lshlrev_b32_e32 v220, 16, v215
	v_add_u32_e32 v221, 0x800, v221
	v_min_i32_e32 v224, 7, v224
	v_min_i32_e32 v225, 7, v225
	v_min_i32_e32 v216, 7, v216
	v_ashrrev_i32_e32 v217, 12, v217
	v_add_u32_e32 v218, 0x800, v218
; __device__ __forceinline__ unsigned cvt_pk_bf16(float lo, float hi) { unsigned r; asm volatile("v_cvt_pk_bf16_f32 %0, %1, %2" : "=v"(r) : "v"(lo), "v"(hi)); return r; }
; #define GAS __attribute__((address_space(1)))
; __device__ __forceinline__ float bf_lo(unsigned w) { return __uint_as_float(w << 16); }
; __device__ __forceinline__ float bf_hi(unsigned w) { return __uint_as_float(w & 0xffff0000u); }
; __device__ __forceinline__ float lo_decode(unsigned hi16, int q4) { return __uint_as_float((hi16 << 16) + (unsigned)(q4 << 12)); }
; template <bool HIN_F32, bool LAST>
; __device__ __forceinline__ void fin_compute(FinStage& S, float* out, bf16_t* HI, unsigned char* LO, float* rs, const f32x4 (&gpv)[4], float coef, int row0, int NGW, int lane) {
;     ...
;         for (int j = 0; j < 2; ++j) { const int idx = 512 * j + 8 * lane; float v[8];
;             const u32x4 fw = S.fw[t][j];
;             if (HIN_F32) {
; #pragma unroll
;                 for (int e = 0; e < 8; ++e) v[e] = S.v[t][j][e >> 2][e & 3];
;             } else { const u32x4 hw = S.hw[t][j]; const unsigned lw = S.lw[t][j];
; #pragma unroll
;                 for (int e = 0; e < 8; ++e) { const unsigned w = hw[e >> 1]; v[e] = lo_decode((e & 1) ? (w >> 16) : (w & 0xffffu), (int)(lw << (28 - 4 * e)) >> 28); } }
; #pragma unroll
;             for (int e = 0; e < 8; ++e) { const unsigned w = fw[e >> 1]; v[e] += ((e & 1) ? bf_hi(w) : bf_lo(w)) * r * gpv[2 * j + (e >> 2)][e & 3]; }
;             if (LAST) { __builtin_nontemporal_store((f32x4){v[0], v[1], v[2], v[3]}, (GAS f32x4*)(out + (size_t)row * DM + idx)); __builtin_nontemporal_store((f32x4){v[4], v[5], v[6], v[7]}, (GAS f32x4*)(out + (size_t)row * DM + idx + 4)); }
;             else { u32x4 hw; hw.x = cvt_pk_bf16(v[0], v[1]); hw.y = cvt_pk_bf16(v[2], v[3]); hw.z = cvt_pk_bf16(v[4], v[5]); hw.w = cvt_pk_bf16(v[6], v[7]);
;                 unsigned lw = 0u;
; #pragma unroll
;                 for (int e = 0; e < 8; ++e) { const unsigned w = hw[e >> 1]; lw |= lo_encode(v[e], (e & 1) ? (w >> 16) : (w & 0xffffu)) << (4 * e); s2 += v[e] * v[e]; }
;                 *(GAS u32x4*)(HI + (size_t)row * DM + idx) = hw; __builtin_nontemporal_store(lw, (GAS unsigned*)(LO + (size_t)row * (DM / 2) + (idx >> 1))); } }
;         if (!LAST) { const float rn = __builtin_amdgcn_rsqf(wave_sum(s2) * (1.0f / DM) + RMS_EPS); if (lane == 0) *(GAS float*)(rs + row) = rn; } }
	v_add_u32_e32 v219, 0x800, v219
	v_sub_u32_e32 v220, v222, v220
	v_ashrrev_i32_e32 v221, 12, v221
	v_and_b32_e32 v224, 15, v224
	v_lshlrev_b32_e32 v225, 4, v225
	v_lshlrev_b32_e32 v216, 8, v216
	v_min_i32_e32 v217, 7, v217
	v_ashrrev_i32_e32 v218, 12, v218
	v_ashrrev_i32_e32 v219, 12, v219
	v_add_u32_e32 v220, 0x800, v220
	v_min_i32_e32 v221, 7, v221
	v_and_b32_e32 v225, 0xf0, v225
	v_and_b32_e32 v216, 0xf00, v216
	v_lshlrev_b32_e32 v217, 12, v217
	v_min_i32_sdwa v218, v218, v192 dst_sel:WORD_1 dst_unused:UNUSED_PAD src0_sel:DWORD src1_sel:DWORD
	v_min_i32_e32 v219, 7, v219
	v_ashrrev_i32_e32 v220, 12, v220
	v_lshl_or_b32 v221, v221, 28, v224
	v_and_b32_e32 v217, 0xf000, v217
	v_and_b32_e32 v218, 0xf0000, v218
	v_lshlrev_b32_e32 v219, 20, v219
	v_min_i32_sdwa v220, v220, v192 dst_sel:BYTE_3 dst_unused:UNUSED_PAD src0_sel:DWORD src1_sel:DWORD
	v_or3_b32 v216, v221, v225, v216
	v_and_b32_e32 v219, 0xf00000, v219
	v_and_b32_e32 v220, 0xf000000, v220
	v_or3_b32 v216, v216, v217, v218
	v_or3_b32 v220, v216, v219, v220
	v_lshl_add_u64 v[216:217], s[42:43], 0, v[170:171]
	v_add_co_u32_e32 v216, vcc, s9, v216
	s_mov_b32 s9, 0x32a00000
	s_nop 0
	v_addc_co_u32_e32 v217, vcc, 0, v217, vcc
	global_store_dwordx4 v[216:217], v[212:215], off
	v_fmac_f32_e32 v226, v222, v222
	v_fmac_f32_e32 v226, v223, v223
	v_lshl_add_u64 v[212:213], s[42:43], 0, v[160:161]
	v_add_co_u32_e32 v218, vcc, s9, v212
	v_lshlrev_b32_e32 v212, 28, v206
	s_nop 0
	v_addc_co_u32_e32 v219, vcc, 0, v213, vcc
	v_ashrrev_i32_e32 v212, 16, v212
	v_lshlrev_b32_e32 v213, 24, v206
	global_store_dword v[218:219], v220, off nt
	v_lshl_add_u32 v220, v114, 16, v212
	v_and_b32_e32 v212, 0xffff0000, v114
	v_and_b32_sdwa v213, sext(v213), s57 dst_sel:DWORD dst_unused:UNUSED_PAD src0_sel:WORD_1 src1_sel:DWORD
	v_add_u32_e32 v221, v212, v213
	v_lshlrev_b32_e32 v212, 20, v206
	v_and_b32_sdwa v212, sext(v212), s57 dst_sel:DWORD dst_unused:UNUSED_PAD src0_sel:WORD_1 src1_sel:DWORD
	v_lshl_add_u32 v222, v115, 16, v212
	v_and_b32_e32 v212, 0xffff0000, v115
	v_and_b32_sdwa v213, sext(v206), s57 dst_sel:DWORD dst_unused:UNUSED_PAD src0_sel:WORD_0 src1_sel:DWORD
	v_add_u32_e32 v223, v212, v213
	v_bfe_i32 v212, v206, 4, 16
	v_and_b32_e32 v212, 0xfffff000, v212
	v_bfe_i32 v213, v206, 8, 16
	v_lshl_add_u32 v224, v116, 16, v212
	v_and_b32_e32 v212, 0xffff0000, v116
	v_and_b32_e32 v213, 0xfffff000, v213
	v_add_u32_e32 v225, v212, v213
	v_bfe_i32 v212, v206, 12, 16
	v_and_b32_e32 v212, 0xfffff000, v212
	v_lshl_add_u32 v227, v117, 16, v212
	v_and_b32_e32 v212, 0xffff0000, v117
	v_and_b32_sdwa v213, sext(v206), s57 dst_sel:DWORD dst_unused:UNUSED_PAD src0_sel:WORD_1 src1_sel:DWORD
	v_add_u32_e32 v228, v212, v213
	v_lshlrev_b32_e32 v212, 16, v126
	v_mul_f32_e32 v212, v211, v212
	v_fmac_f32_e32 v220, v12, v212
	v_and_b32_e32 v212, 0xffff0000, v126
	v_mul_f32_e32 v212, v211, v212
	v_fmac_f32_e32 v221, v13, v212
	v_lshlrev_b32_e32 v212, 16, v127
	v_mul_f32_e32 v212, v211, v212
	v_fmac_f32_e32 v222, v14, v212
	v_and_b32_e32 v212, 0xffff0000, v127
	v_mul_f32_e32 v212, v211, v212
	v_fmac_f32_e32 v223, v15, v212
	v_lshlrev_b32_e32 v212, 16, v128
	v_mul_f32_e32 v212, v211, v212
	v_fmac_f32_e32 v224, v8, v212
	v_and_b32_e32 v212, 0xffff0000, v128
	v_mul_f32_e32 v212, v211, v212
	v_fmac_f32_e32 v225, v9, v212
	v_lshlrev_b32_e32 v212, 16, v129
	v_mul_f32_e32 v212, v211, v212
	v_fmac_f32_e32 v227, v10, v212
	v_and_b32_e32 v212, 0xffff0000, v129
	v_mul_f32_e32 v211, v211, v212
	v_fmac_f32_e32 v228, v11, v211
	v_cvt_pk_bf16_f32 v212, v220, v221
	v_fmac_f32_e32 v226, v220, v220
	v_lshlrev_b32_e32 v211, 16, v212
	v_sub_u32_e32 v211, v220, v211
	v_and_b32_e32 v220, 0xffff0000, v212
	v_cvt_pk_bf16_f32 v213, v222, v223
	v_sub_u32_e32 v220, v221, v220
	v_fmac_f32_e32 v226, v221, v221
	v_lshlrev_b32_e32 v221, 16, v213
	v_sub_u32_e32 v221, v222, v221
	v_fmac_f32_e32 v226, v222, v222
	v_and_b32_e32 v222, 0xffff0000, v213
	v_cvt_pk_bf16_f32 v214, v224, v225
	v_sub_u32_e32 v222, v223, v222
	v_fmac_f32_e32 v226, v223, v223
	v_lshlrev_b32_e32 v223, 16, v214
	v_sub_u32_e32 v223, v224, v223
	v_fmac_f32_e32 v226, v224, v224
	v_and_b32_e32 v224, 0xffff0000, v214
	v_cvt_pk_bf16_f32 v215, v227, v228
	v_sub_u32_e32 v224, v225, v224
	v_fmac_f32_e32 v226, v225, v225
	v_lshlrev_b32_e32 v225, 16, v215
	v_sub_u32_e32 v225, v227, v225
	v_fmac_f32_e32 v226, v227, v227
	v_and_b32_e32 v227, 0xffff0000, v215
	v_add_u32_e32 v211, 0x800, v211
	v_add_u32_e32 v220, 0x800, v220
	v_add_u32_e32 v221, 0x800, v221
	v_sub_u32_e32 v227, v228, v227
	v_ashrrev_i32_e32 v211, 12, v211
	v_ashrrev_i32_e32 v220, 12, v220
	v_ashrrev_i32_e32 v221, 12, v221
	v_add_u32_e32 v222, 0x800, v222
	v_add_u32_e32 v227, 0x800, v227
	v_min_i32_e32 v211, 7, v211
	v_min_i32_e32 v220, 7, v220
	v_min_i32_e32 v221, 7, v221
	v_ashrrev_i32_e32 v222, 12, v222
	v_add_u32_e32 v223, 0x800, v223
	v_add_u32_e32 v224, 0x800, v224
	v_ashrrev_i32_e32 v227, 12, v227
	v_and_b32_e32 v211, 15, v211
	v_lshlrev_b32_e32 v220, 4, v220
	v_lshlrev_b32_e32 v221, 8, v221
	v_min_i32_e32 v222, 7, v222
	v_ashrrev_i32_e32 v223, 12, v223
	v_ashrrev_i32_e32 v224, 12, v224
	v_add_u32_e32 v225, 0x800, v225
	v_min_i32_e32 v227, 7, v227
	v_and_b32_e32 v220, 0xf0, v220
	v_and_b32_e32 v221, 0xf00, v221
	v_lshlrev_b32_e32 v222, 12, v222
	v_min_i32_sdwa v223, v223, v192 dst_sel:WORD_1 dst_unused:UNUSED_PAD src0_sel:DWORD src1_sel:DWORD
	v_min_i32_e32 v224, 7, v224
	v_ashrrev_i32_e32 v225, 12, v225
	v_lshl_or_b32 v211, v227, 28, v211
	v_and_b32_e32 v222, 0xf000, v222
	v_and_b32_e32 v223, 0xf0000, v223
	v_lshlrev_b32_e32 v224, 20, v224
	v_min_i32_sdwa v225, v225, v192 dst_sel:BYTE_3 dst_unused:UNUSED_PAD src0_sel:DWORD src1_sel:DWORD
	v_or3_b32 v211, v211, v220, v221
	v_and_b32_e32 v224, 0xf00000, v224
	v_and_b32_e32 v225, 0xf000000, v225
	v_or3_b32 v211, v211, v222, v223
	v_or3_b32 v211, v211, v224, v225
	v_fmac_f32_e32 v226, v228, v228
	global_store_dwordx4 v[216:217], v[212:215], off offset:1024
	global_store_dword v[218:219], v211, off offset:256 nt
	ds_bpermute_b32 v211, v184, v226
	s_waitcnt lgkmcnt(0)
	v_add_f32_e32 v211, v226, v211
	ds_bpermute_b32 v212, v185, v211
	s_waitcnt lgkmcnt(0)
	v_add_f32_e32 v211, v211, v212
	ds_bpermute_b32 v212, v195, v211
	s_waitcnt lgkmcnt(0)
	v_add_f32_e32 v211, v211, v212
	ds_bpermute_b32 v212, v196, v211
	s_waitcnt lgkmcnt(0)
	v_add_f32_e32 v211, v211, v212
	ds_bpermute_b32 v212, v197, v211
	s_waitcnt lgkmcnt(0)
	v_add_f32_e32 v211, v211, v212
	ds_bpermute_b32 v212, v198, v211
	s_and_saveexec_b64 s[44:45], s[40:41]
	s_cbranch_execz .LBB0_277
	s_waitcnt lgkmcnt(0)
	v_add_f32_e32 v211, v211, v212
	v_fmamk_f32 v211, v211, 0x3a800000, v188
	v_rsq_f32_e32 v211, v211
	s_add_u32 s46, s42, s7
	s_addc_u32 s47, s43, s82
	global_store_dword v32, v211, s[46:47]
; __device__ __forceinline__ unsigned cvt_pk_bf16(float lo, float hi) { unsigned r; asm volatile("v_cvt_pk_bf16_f32 %0, %1, %2" : "=v"(r) : "v"(lo), "v"(hi)); return r; }
; #define GAS __attribute__((address_space(1)))
; __device__ __forceinline__ float bf_lo(unsigned w) { return __uint_as_float(w << 16); }
; template <bool HIN_F32, bool LAST>
; __device__ __forceinline__ void fin_compute(FinStage& S, float* out, bf16_t* HI, unsigned char* LO, float* rs, const f32x4 (&gpv)[4], float coef, int row0, int NGW, int lane) {
;     ...
;     for (int t = 0; t < 2; ++t) { const int row = row0 + t * NGW; float s2 = 0.f;
;         float tot = S.sp[t];
; #pragma unroll
;         for (int o = 1; o < 16; o <<= 1) tot += __shfl_xor(tot, o);
;         const float r = coef * __builtin_amdgcn_rsqf(tot * (1.0f / DM) + RMS_EPS);
; #pragma unroll
;         for (int j = 0; j < 2; ++j) { const int idx = 512 * j + 8 * lane; float v[8];
;             const u32x4 fw = S.fw[t][j];
;             if (HIN_F32) {
; #pragma unroll
;                 for (int e = 0; e < 8; ++e) v[e] = S.v[t][j][e >> 2][e & 3];
;             } else { const u32x4 hw = S.hw[t][j]; const unsigned lw = S.lw[t][j];
; #pragma unroll
;                 for (int e = 0; e < 8; ++e) { const unsigned w = hw[e >> 1]; v[e] = lo_decode((e & 1) ? (w >> 16) : (w & 0xffffu), (int)(lw << (28 - 4 * e)) >> 28); } }
; #pragma unroll
;             for (int e = 0; e < 8; ++e) { const unsigned w = fw[e >> 1]; v[e] += ((e & 1) ? bf_hi(w) : bf_lo(w)) * r * gpv[2 * j + (e >> 2)][e & 3]; }
;             if (LAST) { __builtin_nontemporal_store((f32x4){v[0], v[1], v[2], v[3]}, (GAS f32x4*)(out + (size_t)row * DM + idx)); __builtin_nontemporal_store((f32x4){v[4], v[5], v[6], v[7]}, (GAS f32x4*)(out + (size_t)row * DM + idx + 4)); }
;             else { u32x4 hw; hw.x = cvt_pk_bf16(v[0], v[1]); hw.y = cvt_pk_bf16(v[2], v[3]); hw.z = cvt_pk_bf16(v[4], v[5]); hw.w = cvt_pk_bf16(v[6], v[7]);
;                 unsigned lw = 0u;
; #pragma unroll
;                 for (int e = 0; e < 8; ++e) { const unsigned w = hw[e >> 1]; lw |= lo_encode(v[e], (e & 1) ? (w >> 16) : (w & 0xffffu)) << (4 * e); s2 += v[e] * v[e]; }
;                 *(GAS u32x4*)(HI + (size_t)row * DM + idx) = hw; __builtin_nontemporal_store(lw, (GAS unsigned*)(LO + (size_t)row * (DM / 2) + (idx >> 1))); } }
.LBB0_277:
	s_or_b64 exec, exec, s[44:45]
	ds_bpermute_b32 v211, v184, v208
	v_lshlrev_b32_e32 v213, 24, v207
	v_and_b32_sdwa v213, sext(v213), s57 dst_sel:DWORD dst_unused:UNUSED_PAD src0_sel:WORD_1 src1_sel:DWORD
	s_add_i32 s44, s61, s83
	s_ashr_i32 s45, s44, 31
	s_waitcnt lgkmcnt(0)
	v_add_f32_e32 v211, v208, v211
	ds_bpermute_b32 v212, v185, v211
	s_lshl_b64 s[48:49], s[44:45], 11
	s_lshl_b64 s[46:47], s[44:45], 9
	s_add_u32 s46, s0, s46
	s_addc_u32 s47, s50, s47
	s_waitcnt lgkmcnt(0)
	v_add_f32_e32 v211, v211, v212
	ds_bpermute_b32 v212, v195, v211
	s_waitcnt lgkmcnt(0)
	v_add_f32_e32 v211, v211, v212
	ds_bpermute_b32 v212, v196, v211
	s_waitcnt lgkmcnt(0)
	v_add_f32_e32 v211, v211, v212
	v_lshlrev_b32_e32 v212, 28, v207
	v_ashrrev_i32_e32 v212, 16, v212
	v_lshl_add_u32 v216, v142, 16, v212
	v_and_b32_e32 v212, 0xffff0000, v142
	v_add_u32_e32 v217, v212, v213
	v_lshlrev_b32_e32 v212, 20, v207
	v_and_b32_sdwa v212, sext(v212), s57 dst_sel:DWORD dst_unused:UNUSED_PAD src0_sel:WORD_1 src1_sel:DWORD
	v_lshl_add_u32 v218, v143, 16, v212
	v_and_b32_e32 v212, 0xffff0000, v143
	v_and_b32_sdwa v213, sext(v207), s57 dst_sel:DWORD dst_unused:UNUSED_PAD src0_sel:WORD_0 src1_sel:DWORD
	v_add_u32_e32 v219, v212, v213
	v_bfe_i32 v212, v207, 4, 16
	v_fmamk_f32 v211, v211, 0x3a800000, v188
	v_and_b32_e32 v212, 0xfffff000, v212
	v_bfe_i32 v213, v207, 8, 16
	v_rsq_f32_e32 v211, v211
	v_lshl_add_u32 v220, v144, 16, v212
	v_and_b32_e32 v212, 0xffff0000, v144
	v_and_b32_e32 v213, 0xfffff000, v213
	v_add_u32_e32 v221, v212, v213
	v_bfe_i32 v212, v207, 12, 16
	v_and_b32_e32 v212, 0xfffff000, v212
	v_lshl_add_u32 v222, v145, 16, v212
	v_and_b32_e32 v212, 0xffff0000, v145
	v_and_b32_sdwa v213, sext(v207), s57 dst_sel:DWORD dst_unused:UNUSED_PAD src0_sel:WORD_1 src1_sel:DWORD
	v_mul_f32_e32 v211, v33, v211
	v_add_u32_e32 v223, v212, v213
	v_lshlrev_b32_e32 v212, 16, v130
	v_mul_f32_e32 v212, v211, v212
	v_fmac_f32_e32 v216, v4, v212
	v_and_b32_e32 v212, 0xffff0000, v130
	v_mul_f32_e32 v212, v211, v212
	v_fmac_f32_e32 v217, v5, v212
	v_lshlrev_b32_e32 v212, 16, v131
	v_mul_f32_e32 v212, v211, v212
	v_fmac_f32_e32 v218, v6, v212
	v_and_b32_e32 v212, 0xffff0000, v131
	v_mul_f32_e32 v212, v211, v212
	v_fmac_f32_e32 v219, v7, v212
	v_lshlrev_b32_e32 v212, 16, v132
	v_mul_f32_e32 v212, v211, v212
	v_fmac_f32_e32 v220, v0, v212
	v_and_b32_e32 v212, 0xffff0000, v132
	v_mul_f32_e32 v212, v211, v212
	v_fmac_f32_e32 v221, v1, v212
	v_lshlrev_b32_e32 v212, 16, v133
	v_mul_f32_e32 v212, v211, v212
	v_fmac_f32_e32 v222, v2, v212
	v_and_b32_e32 v212, 0xffff0000, v133
	v_mul_f32_e32 v226, v217, v217
	v_mul_f32_e32 v212, v211, v212
	v_fmac_f32_e32 v226, v216, v216
	v_fmac_f32_e32 v223, v3, v212
	v_cvt_pk_bf16_f32 v212, v216, v217
	v_fmac_f32_e32 v226, v218, v218
	v_and_b32_e32 v225, 0xffff0000, v212
	v_cvt_pk_bf16_f32 v213, v218, v219
	v_lshlrev_b32_e32 v224, 16, v212
	v_sub_u32_e32 v225, v217, v225
	v_and_b32_e32 v217, 0xffff0000, v213
	v_fmac_f32_e32 v226, v219, v219
	v_cvt_pk_bf16_f32 v214, v220, v221
	v_sub_u32_e32 v224, v216, v224
	v_lshlrev_b32_e32 v216, 16, v213
	v_sub_u32_e32 v217, v219, v217
	v_fmac_f32_e32 v226, v220, v220
	v_and_b32_e32 v219, 0xffff0000, v214
	v_cvt_pk_bf16_f32 v215, v222, v223
	v_sub_u32_e32 v216, v218, v216
	v_sub_u32_e32 v219, v221, v219
	v_fmac_f32_e32 v226, v221, v221
	v_and_b32_e32 v221, 0xffff0000, v215
	v_add_u32_e32 v224, 0x800, v224
	v_add_u32_e32 v225, 0x800, v225
	v_add_u32_e32 v216, 0x800, v216
	v_lshlrev_b32_e32 v218, 16, v214
	v_sub_u32_e32 v221, v223, v221
	v_ashrrev_i32_e32 v224, 12, v224
	v_ashrrev_i32_e32 v225, 12, v225
	v_ashrrev_i32_e32 v216, 12, v216
	v_add_u32_e32 v217, 0x800, v217
	v_sub_u32_e32 v218, v220, v218
	v_lshlrev_b32_e32 v220, 16, v215
	v_add_u32_e32 v221, 0x800, v221
	v_min_i32_e32 v224, 7, v224
	v_min_i32_e32 v225, 7, v225
	v_min_i32_e32 v216, 7, v216
	v_ashrrev_i32_e32 v217, 12, v217
	v_add_u32_e32 v218, 0x800, v218
	v_add_u32_e32 v219, 0x800, v219
	v_sub_u32_e32 v220, v222, v220
	v_ashrrev_i32_e32 v221, 12, v221
	v_and_b32_e32 v224, 15, v224
	v_lshlrev_b32_e32 v225, 4, v225
	v_lshlrev_b32_e32 v216, 8, v216
	v_min_i32_e32 v217, 7, v217
	v_ashrrev_i32_e32 v218, 12, v218
	v_ashrrev_i32_e32 v219, 12, v219
	v_add_u32_e32 v220, 0x800, v220
	v_min_i32_e32 v221, 7, v221
	v_and_b32_e32 v225, 0xf0, v225
	v_and_b32_e32 v216, 0xf00, v216
	v_lshlrev_b32_e32 v217, 12, v217
	v_min_i32_sdwa v218, v218, v192 dst_sel:WORD_1 dst_unused:UNUSED_PAD src0_sel:DWORD src1_sel:DWORD
	v_min_i32_e32 v219, 7, v219
	v_ashrrev_i32_e32 v220, 12, v220
	v_lshl_or_b32 v221, v221, 28, v224
	v_and_b32_e32 v217, 0xf000, v217
	v_and_b32_e32 v218, 0xf0000, v218
	v_lshlrev_b32_e32 v219, 20, v219
	v_min_i32_sdwa v220, v220, v192 dst_sel:BYTE_3 dst_unused:UNUSED_PAD src0_sel:DWORD src1_sel:DWORD
	v_or3_b32 v216, v221, v225, v216
	v_and_b32_e32 v219, 0xf00000, v219
	v_and_b32_e32 v220, 0xf000000, v220
	v_or3_b32 v216, v216, v217, v218
	v_or3_b32 v218, v216, v219, v220
	v_lshl_add_u64 v[216:217], v[156:157], 0, s[48:49]
	global_store_dwordx4 v[216:217], v[212:215], off
	v_fmac_f32_e32 v226, v222, v222
	v_fmac_f32_e32 v226, v223, v223
	v_lshl_add_u64 v[212:213], s[46:47], 0, v[152:153]
	global_store_dword v[212:213], v218, off nt
	v_lshlrev_b32_e32 v212, 28, v209
	v_ashrrev_i32_e32 v212, 16, v212
	v_lshlrev_b32_e32 v213, 24, v209
	v_lshl_add_u32 v218, v138, 16, v212
	v_and_b32_e32 v212, 0xffff0000, v138
	v_and_b32_sdwa v213, sext(v213), s57 dst_sel:DWORD dst_unused:UNUSED_PAD src0_sel:WORD_1 src1_sel:DWORD
	v_add_u32_e32 v219, v212, v213
	v_lshlrev_b32_e32 v212, 20, v209
	v_and_b32_sdwa v212, sext(v212), s57 dst_sel:DWORD dst_unused:UNUSED_PAD src0_sel:WORD_1 src1_sel:DWORD
; __device__ __forceinline__ unsigned cvt_pk_bf16(float lo, float hi) { unsigned r; asm volatile("v_cvt_pk_bf16_f32 %0, %1, %2" : "=v"(r) : "v"(lo), "v"(hi)); return r; }
; #define GAS __attribute__((address_space(1)))
; __device__ __forceinline__ float bf_lo(unsigned w) { return __uint_as_float(w << 16); }
; __device__ __forceinline__ float bf_hi(unsigned w) { return __uint_as_float(w & 0xffff0000u); }
; __device__ __forceinline__ float lo_decode(unsigned hi16, int q4) { return __uint_as_float((hi16 << 16) + (unsigned)(q4 << 12)); }
; template <bool HIN_F32, bool LAST>
; __device__ __forceinline__ void fin_compute(FinStage& S, float* out, bf16_t* HI, unsigned char* LO, float* rs, const f32x4 (&gpv)[4], float coef, int row0, int NGW, int lane) {
;     ...
;         for (int j = 0; j < 2; ++j) { const int idx = 512 * j + 8 * lane; float v[8];
;             const u32x4 fw = S.fw[t][j];
;             if (HIN_F32) {
; #pragma unroll
;                 for (int e = 0; e < 8; ++e) v[e] = S.v[t][j][e >> 2][e & 3];
;             } else { const u32x4 hw = S.hw[t][j]; const unsigned lw = S.lw[t][j];
; #pragma unroll
;                 for (int e = 0; e < 8; ++e) { const unsigned w = hw[e >> 1]; v[e] = lo_decode((e & 1) ? (w >> 16) : (w & 0xffffu), (int)(lw << (28 - 4 * e)) >> 28); } }
; #pragma unroll
;             for (int e = 0; e < 8; ++e) { const unsigned w = fw[e >> 1]; v[e] += ((e & 1) ? bf_hi(w) : bf_lo(w)) * r * gpv[2 * j + (e >> 2)][e & 3]; }
;             if (LAST) { __builtin_nontemporal_store((f32x4){v[0], v[1], v[2], v[3]}, (GAS f32x4*)(out + (size_t)row * DM + idx)); __builtin_nontemporal_store((f32x4){v[4], v[5], v[6], v[7]}, (GAS f32x4*)(out + (size_t)row * DM + idx + 4)); }
;             else { u32x4 hw; hw.x = cvt_pk_bf16(v[0], v[1]); hw.y = cvt_pk_bf16(v[2], v[3]); hw.z = cvt_pk_bf16(v[4], v[5]); hw.w = cvt_pk_bf16(v[6], v[7]);
;                 unsigned lw = 0u;
; #pragma unroll
;                 for (int e = 0; e < 8; ++e) { const unsigned w = hw[e >> 1]; lw |= lo_encode(v[e], (e & 1) ? (w >> 16) : (w & 0xffffu)) << (4 * e); s2 += v[e] * v[e]; }
;                 *(GAS u32x4*)(HI + (size_t)row * DM + idx) = hw; __builtin_nontemporal_store(lw, (GAS unsigned*)(LO + (size_t)row * (DM / 2) + (idx >> 1))); } }
;         if (!LAST) { const float rn = __builtin_amdgcn_rsqf(wave_sum(s2) * (1.0f / DM) + RMS_EPS); if (lane == 0) *(GAS float*)(rs + row) = rn; } }
	v_lshl_add_u32 v220, v139, 16, v212
	v_and_b32_e32 v212, 0xffff0000, v139
	v_and_b32_sdwa v213, sext(v209), s57 dst_sel:DWORD dst_unused:UNUSED_PAD src0_sel:WORD_0 src1_sel:DWORD
	v_add_u32_e32 v221, v212, v213
	v_bfe_i32 v212, v209, 4, 16
	v_and_b32_e32 v212, 0xfffff000, v212
	v_bfe_i32 v213, v209, 8, 16
	v_lshl_add_u32 v222, v140, 16, v212
	v_and_b32_e32 v212, 0xffff0000, v140
	v_and_b32_e32 v213, 0xfffff000, v213
	v_add_u32_e32 v223, v212, v213
	v_bfe_i32 v212, v209, 12, 16
	v_and_b32_e32 v212, 0xfffff000, v212
	v_lshl_add_u32 v224, v141, 16, v212
	v_and_b32_e32 v212, 0xffff0000, v141
	v_and_b32_sdwa v213, sext(v209), s57 dst_sel:DWORD dst_unused:UNUSED_PAD src0_sel:WORD_1 src1_sel:DWORD
	v_add_u32_e32 v225, v212, v213
	v_lshlrev_b32_e32 v212, 16, v134
	v_mul_f32_e32 v212, v211, v212
	v_fmac_f32_e32 v218, v12, v212
	v_and_b32_e32 v212, 0xffff0000, v134
	v_mul_f32_e32 v212, v211, v212
	v_fmac_f32_e32 v219, v13, v212
	v_lshlrev_b32_e32 v212, 16, v135
	v_mul_f32_e32 v212, v211, v212
	v_fmac_f32_e32 v220, v14, v212
	v_and_b32_e32 v212, 0xffff0000, v135
	v_mul_f32_e32 v212, v211, v212
	v_fmac_f32_e32 v221, v15, v212
	v_lshlrev_b32_e32 v212, 16, v136
	v_mul_f32_e32 v212, v211, v212
	v_fmac_f32_e32 v222, v8, v212
	v_and_b32_e32 v212, 0xffff0000, v136
	v_mul_f32_e32 v212, v211, v212
	v_fmac_f32_e32 v223, v9, v212
	v_lshlrev_b32_e32 v212, 16, v137
	v_mul_f32_e32 v212, v211, v212
	v_fmac_f32_e32 v224, v10, v212
	v_and_b32_e32 v212, 0xffff0000, v137
	v_mul_f32_e32 v211, v211, v212
	v_fmac_f32_e32 v225, v11, v211
	v_cvt_pk_bf16_f32 v212, v218, v219
	v_fmac_f32_e32 v226, v218, v218
	v_lshlrev_b32_e32 v211, 16, v212
	v_sub_u32_e32 v211, v218, v211
	v_and_b32_e32 v218, 0xffff0000, v212
	v_cvt_pk_bf16_f32 v213, v220, v221
	v_sub_u32_e32 v218, v219, v218
	v_fmac_f32_e32 v226, v219, v219
	v_lshlrev_b32_e32 v219, 16, v213
	v_sub_u32_e32 v219, v220, v219
	v_fmac_f32_e32 v226, v220, v220
	v_and_b32_e32 v220, 0xffff0000, v213
	v_cvt_pk_bf16_f32 v214, v222, v223
	v_sub_u32_e32 v220, v221, v220
	v_fmac_f32_e32 v226, v221, v221
	v_lshlrev_b32_e32 v221, 16, v214
	v_sub_u32_e32 v221, v222, v221
	v_fmac_f32_e32 v226, v222, v222
	v_and_b32_e32 v222, 0xffff0000, v214
	v_cvt_pk_bf16_f32 v215, v224, v225
	v_sub_u32_e32 v222, v223, v222
	v_fmac_f32_e32 v226, v223, v223
	v_lshlrev_b32_e32 v223, 16, v215
	v_sub_u32_e32 v223, v224, v223
	v_fmac_f32_e32 v226, v224, v224
	v_and_b32_e32 v224, 0xffff0000, v215
	v_add_u32_e32 v211, 0x800, v211
	v_add_u32_e32 v218, 0x800, v218
	v_add_u32_e32 v219, 0x800, v219
	v_sub_u32_e32 v224, v225, v224
	v_ashrrev_i32_e32 v211, 12, v211
	v_ashrrev_i32_e32 v218, 12, v218
	v_ashrrev_i32_e32 v219, 12, v219
	v_add_u32_e32 v220, 0x800, v220
	v_add_u32_e32 v224, 0x800, v224
	v_min_i32_e32 v211, 7, v211
	v_min_i32_e32 v218, 7, v218
	v_min_i32_e32 v219, 7, v219
	v_ashrrev_i32_e32 v220, 12, v220
	v_add_u32_e32 v221, 0x800, v221
	v_add_u32_e32 v222, 0x800, v222
	v_ashrrev_i32_e32 v224, 12, v224
	v_and_b32_e32 v211, 15, v211
	v_lshlrev_b32_e32 v218, 4, v218
	v_lshlrev_b32_e32 v219, 8, v219
	v_min_i32_e32 v220, 7, v220
	v_ashrrev_i32_e32 v221, 12, v221
	v_ashrrev_i32_e32 v222, 12, v222
	v_add_u32_e32 v223, 0x800, v223
	v_min_i32_e32 v224, 7, v224
	v_and_b32_e32 v218, 0xf0, v218
	v_and_b32_e32 v219, 0xf00, v219
	v_lshlrev_b32_e32 v220, 12, v220
	v_min_i32_sdwa v221, v221, v192 dst_sel:WORD_1 dst_unused:UNUSED_PAD src0_sel:DWORD src1_sel:DWORD
	v_min_i32_e32 v222, 7, v222
	v_ashrrev_i32_e32 v223, 12, v223
	v_lshl_or_b32 v211, v224, 28, v211
	v_and_b32_e32 v220, 0xf000, v220
	v_and_b32_e32 v221, 0xf0000, v221
	v_lshlrev_b32_e32 v222, 20, v222
	v_min_i32_sdwa v223, v223, v192 dst_sel:BYTE_3 dst_unused:UNUSED_PAD src0_sel:DWORD src1_sel:DWORD
	v_or3_b32 v211, v211, v218, v219
	v_and_b32_e32 v222, 0xf00000, v222
	v_and_b32_e32 v223, 0xf000000, v223
	v_or3_b32 v211, v211, v220, v221
	v_or3_b32 v211, v211, v222, v223
	v_fmac_f32_e32 v226, v225, v225
	global_store_dwordx4 v[216:217], v[212:215], off offset:1024
	s_nop 1
	v_lshl_add_u64 v[212:213], s[46:47], 0, v[154:155]
	global_store_dword v[212:213], v211, off nt
	ds_bpermute_b32 v211, v184, v226
	s_waitcnt lgkmcnt(0)
	v_add_f32_e32 v211, v226, v211
	ds_bpermute_b32 v212, v185, v211
	s_waitcnt lgkmcnt(0)
	v_add_f32_e32 v211, v211, v212
	ds_bpermute_b32 v212, v195, v211
	s_waitcnt lgkmcnt(0)
	v_add_f32_e32 v211, v211, v212
	ds_bpermute_b32 v212, v196, v211
	s_waitcnt lgkmcnt(0)
	v_add_f32_e32 v211, v211, v212
	ds_bpermute_b32 v212, v197, v211
	s_waitcnt lgkmcnt(0)
	v_add_f32_e32 v211, v211, v212
	ds_bpermute_b32 v212, v198, v211
	s_and_saveexec_b64 s[46:47], s[40:41]
	s_cbranch_execz .LBB0_279
	s_waitcnt lgkmcnt(0)
	v_add_f32_e32 v211, v211, v212
	v_fmamk_f32 v211, v211, 0x3a800000, v188
	v_rsq_f32_e32 v211, v211
	s_lshl_b64 s[44:45], s[44:45], 2
	s_add_u32 s44, s66, s44
	s_addc_u32 s45, s67, s45
	global_store_dword v32, v211, s[44:45]
; #define GAS __attribute__((address_space(1)))
; template <bool HIN_F32>
; __device__ __forceinline__ void fin_load(FinStage& S, const float* x, const bf16_t* HI, const unsigned char* LO, const bf16_t* f, const float* ss, int row0, int NGW, int lane) {
; #pragma unroll
;     for (int t = 0; t < 2; ++t) { const int row = row0 + t * NGW;
; #pragma unroll
;         for (int j = 0; j < 2; ++j) { const int idx = 512 * j + 8 * lane;
;             if (HIN_F32) { S.v[t][j][0] = __builtin_nontemporal_load((const GAS f32x4*)(x + (size_t)row * DM + idx)); S.v[t][j][1] = __builtin_nontemporal_load((const GAS f32x4*)(x + (size_t)row * DM + idx + 4)); }
;             else { S.hw[t][j] = __builtin_nontemporal_load((const GAS u32x4*)(HI + (size_t)row * DM + idx)); S.lw[t][j] = __builtin_nontemporal_load((const GAS unsigned*)(LO + (size_t)row * (DM / 2) + (idx >> 1))); }
;             S.fw[t][j] = __builtin_nontemporal_load((const GAS u32x4*)(f + (size_t)row * DM + idx)); }
;         S.sp[t] = *(const GAS float*)(ss + (size_t)row * 16 + (lane & 15)); }
; template <bool HIN_F32, bool LAST>
; __device__ __forceinline__ void fin_phase(const float* x, float* out, bf16_t* HI, unsigned char* LO, float* rs, const bf16_t* f, const float* ss, const float* gpost, float coef, int gw, int NGW, int rend, int lane) {
;     ...
;         for (int u = 0; u < 3; ++u) {
;             const int rowc = base + 2 * NGW * u, rowl = rowc + 4 * NGW;
;             if (rowl < rend) fin_load<HIN_F32>(S[(u + 2) % 3], x, HI, LO, f, ss, rowl, NGW, lane);
;             if (rowc < rend) fin_compute<HIN_F32, LAST>(S[u], out, HI, LO, rs, gpv, coef, rowc, NGW, lane);
.LBB0_279:
	s_or_b64 exec, exec, s[46:47]
	s_add_i32 s78, s84, s83
	s_cmp_ge_i32 s78, s51
	s_cselect_b64 s[80:81], -1, 0
	s_cselect_b32 s100, 1, s100
	s_and_b64 vcc, exec, s[80:81]
	s_cbranch_vccnz .LBB0_283
	s_ashr_i32 s79, s78, 31
	s_lshl_b64 s[44:45], s[78:79], 9
	s_add_u32 s44, s0, s44
	s_addc_u32 s45, s50, s45
	v_lshl_add_u64 v[110:111], s[44:45], 0, v[152:153]
	v_lshl_add_u64 v[128:129], s[44:45], 0, v[154:155]
	s_lshl_b64 s[44:45], s[78:79], 6
	v_readlane_b32 s9, v253, 47
	v_lshl_add_u64 v[130:131], v[150:151], 0, s[44:45]
	s_add_i32 s44, s9, s83
	s_lshl_b64 s[46:47], s[78:79], 11
	s_ashr_i32 s45, s44, 31
	v_lshl_add_u64 v[114:115], v[156:157], 0, s[46:47]
	v_lshl_add_u64 v[126:127], v[158:159], 0, s[46:47]
	s_lshl_b64 s[46:47], s[44:45], 9
	s_add_u32 s46, s0, s46
	s_addc_u32 s47, s50, s47
	s_lshl_b64 s[48:49], s[44:45], 11
	global_load_dword v204, v[110:111], off nt
	s_nop 0
	global_load_dwordx4 v[110:113], v[126:127], off nt
	global_load_dwordx4 v[118:121], v[114:115], off nt
	s_nop 0
	global_load_dwordx4 v[114:117], v[114:115], off offset:1024 nt
	s_nop 0
	global_load_dword v206, v[128:129], off nt
	global_load_dword v205, v[130:131], off
	s_nop 0
	global_load_dwordx4 v[126:129], v[126:127], off offset:1024 nt
	v_lshl_add_u64 v[134:135], v[156:157], 0, s[48:49]
	v_lshl_add_u64 v[130:131], s[46:47], 0, v[152:153]
	v_lshl_add_u64 v[136:137], v[158:159], 0, s[48:49]
	global_load_dword v207, v[130:131], off nt
	s_nop 0
	global_load_dwordx4 v[130:133], v[136:137], off nt
	global_load_dwordx4 v[142:145], v[134:135], off nt
	global_load_dwordx4 v[138:141], v[134:135], off offset:1024 nt
	v_lshl_add_u64 v[134:135], s[46:47], 0, v[154:155]
	s_lshl_b64 s[44:45], s[44:45], 6
	s_waitcnt lgkmcnt(0)
	v_lshl_add_u64 v[212:213], v[150:151], 0, s[44:45]
	global_load_dword v209, v[134:135], off nt
	global_load_dword v208, v[212:213], off
	s_nop 0
	global_load_dwordx4 v[134:137], v[136:137], off offset:1024 nt
	v_readlane_b32 s79, v253, 32
	v_readlane_b32 s73, v253, 4
	v_readlane_b32 s72, v253, 3
	v_readlane_b32 s61, v253, 49
	s_add_i32 s44, s72, s83
	s_cmp_ge_i32 s44, s51
	s_cbranch_scc0 .LBB0_284
.LBB0_281:
	s_add_i32 s44, s79, s83
	s_cmp_ge_i32 s44, s51
	s_cselect_b32 s100, 1, s100
	s_cbranch_scc1 .LBB0_289

; template <bool HIN_F32, bool LAST>
; __device__ __forceinline__ void fin_phase(const float* x, float* out, bf16_t* HI, unsigned char* LO, float* rs, const bf16_t* f, const float* ss, const float* gpost, float coef, int gw, int NGW, int rend, int lane) {
;     ...
;     for (int base = gw; base < rend; base += 6 * NGW) {
; #pragma unroll
;         for (int u = 0; u < 3; ++u) {
;             const int rowc = base + 2 * NGW * u, rowl = rowc + 4 * NGW;
;             if (rowl < rend) fin_load<HIN_F32>(S[(u + 2) % 3], x, HI, LO, f, ss, rowl, NGW, lane);
;             if (rowc < rend) fin_compute<HIN_F32, LAST>(S[u], out, HI, LO, rs, gpv, coef, rowc, NGW, lane);
.LBB0_288:
	s_or_b64 exec, exec, s[46:47]
	s_add_i32 s44, s79, s83
	s_cmp_ge_i32 s44, s51
	s_cselect_b32 s100, 1, s100
	s_cbranch_scc0 .LBB0_282

; __device__ __forceinline__ float bf_lo(unsigned w) { return __uint_as_float(w << 16); }
; __device__ __forceinline__ float bf_hi(unsigned w) { return __uint_as_float(w & 0xffff0000u); }
; __device__ __forceinline__ float lo_decode(unsigned hi16, int q4) { return __uint_as_float((hi16 << 16) + (unsigned)(q4 << 12)); }
; template <bool HIN_F32, bool LAST>
; __device__ __forceinline__ void fin_compute(FinStage& S, float* out, bf16_t* HI, unsigned char* LO, float* rs, const f32x4 (&gpv)[4], float coef, int row0, int NGW, int lane) {
;     ...
;     for (int t = 0; t < 2; ++t) { const int row = row0 + t * NGW; float s2 = 0.f;
;         float tot = S.sp[t];
; #pragma unroll
;         for (int o = 1; o < 16; o <<= 1) tot += __shfl_xor(tot, o);
;         const float r = coef * __builtin_amdgcn_rsqf(tot * (1.0f / DM) + RMS_EPS);
; #pragma unroll
;         for (int j = 0; j < 2; ++j) { const int idx = 512 * j + 8 * lane; float v[8];
;             const u32x4 fw = S.fw[t][j];
;             if (HIN_F32) {
; #pragma unroll
;                 for (int e = 0; e < 8; ++e) v[e] = S.v[t][j][e >> 2][e & 3];
;             } else { const u32x4 hw = S.hw[t][j]; const unsigned lw = S.lw[t][j];
; #pragma unroll
;                 for (int e = 0; e < 8; ++e) { const unsigned w = hw[e >> 1]; v[e] = lo_decode((e & 1) ? (w >> 16) : (w & 0xffffu), (int)(lw << (28 - 4 * e)) >> 28); } }
; #pragma unroll
;             for (int e = 0; e < 8; ++e) { const unsigned w = fw[e >> 1]; v[e] += ((e & 1) ? bf_hi(w) : bf_lo(w)) * r * gpv[2 * j + (e >> 2)][e & 3]; }
.Lfin_mid_R_go:
	ds_bpermute_b32 v211, v184, v202
	v_lshlrev_b32_e32 v213, 24, v199
	v_and_b32_sdwa v213, sext(v213), s57 dst_sel:DWORD dst_unused:UNUSED_PAD src0_sel:WORD_1 src1_sel:DWORD
	s_ashr_i32 s9, s8, 31
	s_lshl_b64 s[46:47], s[8:9], 11
	s_waitcnt lgkmcnt(0)
	v_add_f32_e32 v211, v202, v211
	ds_bpermute_b32 v212, v185, v211
	s_lshl_b64 s[44:45], s[8:9], 9
	s_add_u32 s44, s0, s44
	s_addc_u32 s45, s50, s45
	s_waitcnt lgkmcnt(0)
	v_add_f32_e32 v211, v211, v212
	ds_bpermute_b32 v212, v195, v211
	s_waitcnt lgkmcnt(0)
	v_add_f32_e32 v211, v211, v212
	ds_bpermute_b32 v212, v196, v211
	s_waitcnt lgkmcnt(0)
	v_add_f32_e32 v211, v211, v212
	v_lshlrev_b32_e32 v212, 28, v199
	v_ashrrev_i32_e32 v212, 16, v212
	v_lshl_add_u32 v216, v94, 16, v212
	v_and_b32_e32 v212, 0xffff0000, v94
	v_add_u32_e32 v217, v212, v213
	v_lshlrev_b32_e32 v212, 20, v199
	v_and_b32_sdwa v212, sext(v212), s57 dst_sel:DWORD dst_unused:UNUSED_PAD src0_sel:WORD_1 src1_sel:DWORD
	v_lshl_add_u32 v218, v95, 16, v212
	v_and_b32_e32 v212, 0xffff0000, v95
	v_and_b32_sdwa v213, sext(v199), s57 dst_sel:DWORD dst_unused:UNUSED_PAD src0_sel:WORD_0 src1_sel:DWORD
	v_add_u32_e32 v219, v212, v213
	v_bfe_i32 v212, v199, 4, 16
	v_fmamk_f32 v211, v211, 0x3a800000, v188
	v_and_b32_e32 v212, 0xfffff000, v212
	v_bfe_i32 v213, v199, 8, 16
	v_rsq_f32_e32 v211, v211
	v_lshl_add_u32 v220, v96, 16, v212
	v_and_b32_e32 v212, 0xffff0000, v96
	v_and_b32_e32 v213, 0xfffff000, v213
	v_add_u32_e32 v221, v212, v213
	v_bfe_i32 v212, v199, 12, 16
	v_and_b32_e32 v212, 0xfffff000, v212
	v_lshl_add_u32 v222, v97, 16, v212
	v_and_b32_e32 v212, 0xffff0000, v97
	v_and_b32_sdwa v213, sext(v199), s57 dst_sel:DWORD dst_unused:UNUSED_PAD src0_sel:WORD_1 src1_sel:DWORD
	v_mul_f32_e32 v211, v33, v211
	v_add_u32_e32 v223, v212, v213
	v_lshlrev_b32_e32 v212, 16, v82
	v_mul_f32_e32 v212, v211, v212
	v_fmac_f32_e32 v216, v4, v212
	v_and_b32_e32 v212, 0xffff0000, v82
	v_mul_f32_e32 v212, v211, v212
	v_fmac_f32_e32 v217, v5, v212
	v_lshlrev_b32_e32 v212, 16, v83
	v_mul_f32_e32 v212, v211, v212
	v_fmac_f32_e32 v218, v6, v212
	v_and_b32_e32 v212, 0xffff0000, v83
	v_mul_f32_e32 v212, v211, v212
	v_fmac_f32_e32 v219, v7, v212
	v_lshlrev_b32_e32 v212, 16, v84
	v_mul_f32_e32 v212, v211, v212
	v_fmac_f32_e32 v220, v0, v212
	v_and_b32_e32 v212, 0xffff0000, v84
	v_mul_f32_e32 v212, v211, v212
	v_fmac_f32_e32 v221, v1, v212
	v_lshlrev_b32_e32 v212, 16, v85
	v_mul_f32_e32 v212, v211, v212
	v_fmac_f32_e32 v222, v2, v212
	v_and_b32_e32 v212, 0xffff0000, v85
	v_mul_f32_e32 v226, v217, v217
	v_mul_f32_e32 v212, v211, v212
	v_fmac_f32_e32 v226, v216, v216
	v_fmac_f32_e32 v223, v3, v212
	v_cvt_pk_bf16_f32 v212, v216, v217
	v_fmac_f32_e32 v226, v218, v218
	v_and_b32_e32 v225, 0xffff0000, v212
	v_cvt_pk_bf16_f32 v213, v218, v219
	v_lshlrev_b32_e32 v224, 16, v212
	v_sub_u32_e32 v225, v217, v225
	v_and_b32_e32 v217, 0xffff0000, v213
	v_fmac_f32_e32 v226, v219, v219
	v_cvt_pk_bf16_f32 v214, v220, v221
	v_sub_u32_e32 v224, v216, v224
	v_lshlrev_b32_e32 v216, 16, v213
	v_sub_u32_e32 v217, v219, v217
	v_fmac_f32_e32 v226, v220, v220
	v_and_b32_e32 v219, 0xffff0000, v214
	v_cvt_pk_bf16_f32 v215, v222, v223
	v_sub_u32_e32 v216, v218, v216
	v_sub_u32_e32 v219, v221, v219
	v_fmac_f32_e32 v226, v221, v221
	v_and_b32_e32 v221, 0xffff0000, v215
	v_add_u32_e32 v224, 0x800, v224
	v_add_u32_e32 v225, 0x800, v225
	v_add_u32_e32 v216, 0x800, v216
	v_lshlrev_b32_e32 v218, 16, v214
	v_sub_u32_e32 v221, v223, v221
	v_ashrrev_i32_e32 v224, 12, v224
	v_ashrrev_i32_e32 v225, 12, v225
	v_ashrrev_i32_e32 v216, 12, v216
	v_add_u32_e32 v217, 0x800, v217
	v_sub_u32_e32 v218, v220, v218
	v_lshlrev_b32_e32 v220, 16, v215
	v_add_u32_e32 v221, 0x800, v221
	v_min_i32_e32 v224, 7, v224
	v_min_i32_e32 v225, 7, v225
	v_min_i32_e32 v216, 7, v216
	v_ashrrev_i32_e32 v217, 12, v217
	v_add_u32_e32 v218, 0x800, v218
	v_add_u32_e32 v219, 0x800, v219
	v_sub_u32_e32 v220, v222, v220
	v_ashrrev_i32_e32 v221, 12, v221
	v_and_b32_e32 v224, 15, v224
	v_lshlrev_b32_e32 v225, 4, v225
	v_lshlrev_b32_e32 v216, 8, v216
	v_min_i32_e32 v217, 7, v217
	v_ashrrev_i32_e32 v218, 12, v218
	v_ashrrev_i32_e32 v219, 12, v219
	v_add_u32_e32 v220, 0x800, v220
	v_min_i32_e32 v221, 7, v221
	v_and_b32_e32 v225, 0xf0, v225
	v_and_b32_e32 v216, 0xf00, v216
	v_lshlrev_b32_e32 v217, 12, v217
	v_min_i32_sdwa v218, v218, v192 dst_sel:WORD_1 dst_unused:UNUSED_PAD src0_sel:DWORD src1_sel:DWORD
	v_min_i32_e32 v219, 7, v219
	v_ashrrev_i32_e32 v220, 12, v220
	v_lshl_or_b32 v221, v221, 28, v224
	v_and_b32_e32 v217, 0xf000, v217
	v_and_b32_e32 v218, 0xf0000, v218
	v_lshlrev_b32_e32 v219, 20, v219
	v_min_i32_sdwa v220, v220, v192 dst_sel:BYTE_3 dst_unused:UNUSED_PAD src0_sel:DWORD src1_sel:DWORD
	v_or3_b32 v216, v221, v225, v216
	v_and_b32_e32 v219, 0xf00000, v219
	v_and_b32_e32 v220, 0xf000000, v220
	v_or3_b32 v216, v216, v217, v218
	v_or3_b32 v218, v216, v219, v220
	v_lshl_add_u64 v[216:217], v[156:157], 0, s[46:47]
	global_store_dwordx4 v[216:217], v[212:215], off
	v_fmac_f32_e32 v226, v222, v222
	v_fmac_f32_e32 v226, v223, v223
	v_lshl_add_u64 v[212:213], s[44:45], 0, v[152:153]
	global_store_dword v[212:213], v218, off nt
	v_lshlrev_b32_e32 v212, 28, v200
	v_ashrrev_i32_e32 v212, 16, v212
	v_lshlrev_b32_e32 v213, 24, v200
	v_lshl_add_u32 v218, v90, 16, v212
	v_and_b32_e32 v212, 0xffff0000, v90
	v_and_b32_sdwa v213, sext(v213), s57 dst_sel:DWORD dst_unused:UNUSED_PAD src0_sel:WORD_1 src1_sel:DWORD
	v_add_u32_e32 v219, v212, v213
	v_lshlrev_b32_e32 v212, 20, v200
	v_and_b32_sdwa v212, sext(v212), s57 dst_sel:DWORD dst_unused:UNUSED_PAD src0_sel:WORD_1 src1_sel:DWORD
	v_lshl_add_u32 v220, v91, 16, v212
; __device__ __forceinline__ unsigned cvt_pk_bf16(float lo, float hi) { unsigned r; asm volatile("v_cvt_pk_bf16_f32 %0, %1, %2" : "=v"(r) : "v"(lo), "v"(hi)); return r; }
; #define GAS __attribute__((address_space(1)))
; __device__ __forceinline__ float bf_lo(unsigned w) { return __uint_as_float(w << 16); }
; __device__ __forceinline__ float bf_hi(unsigned w) { return __uint_as_float(w & 0xffff0000u); }
; __device__ __forceinline__ float lo_decode(unsigned hi16, int q4) { return __uint_as_float((hi16 << 16) + (unsigned)(q4 << 12)); }
; template <bool HIN_F32, bool LAST>
; __device__ __forceinline__ void fin_compute(FinStage& S, float* out, bf16_t* HI, unsigned char* LO, float* rs, const f32x4 (&gpv)[4], float coef, int row0, int NGW, int lane) {
;     ...
;         for (int j = 0; j < 2; ++j) { const int idx = 512 * j + 8 * lane; float v[8];
;             const u32x4 fw = S.fw[t][j];
;             if (HIN_F32) {
; #pragma unroll
;                 for (int e = 0; e < 8; ++e) v[e] = S.v[t][j][e >> 2][e & 3];
;             } else { const u32x4 hw = S.hw[t][j]; const unsigned lw = S.lw[t][j];
; #pragma unroll
;                 for (int e = 0; e < 8; ++e) { const unsigned w = hw[e >> 1]; v[e] = lo_decode((e & 1) ? (w >> 16) : (w & 0xffffu), (int)(lw << (28 - 4 * e)) >> 28); } }
; #pragma unroll
;             for (int e = 0; e < 8; ++e) { const unsigned w = fw[e >> 1]; v[e] += ((e & 1) ? bf_hi(w) : bf_lo(w)) * r * gpv[2 * j + (e >> 2)][e & 3]; }
;             if (LAST) { __builtin_nontemporal_store((f32x4){v[0], v[1], v[2], v[3]}, (GAS f32x4*)(out + (size_t)row * DM + idx)); __builtin_nontemporal_store((f32x4){v[4], v[5], v[6], v[7]}, (GAS f32x4*)(out + (size_t)row * DM + idx + 4)); }
;             else { u32x4 hw; hw.x = cvt_pk_bf16(v[0], v[1]); hw.y = cvt_pk_bf16(v[2], v[3]); hw.z = cvt_pk_bf16(v[4], v[5]); hw.w = cvt_pk_bf16(v[6], v[7]);
;                 unsigned lw = 0u;
; #pragma unroll
;                 for (int e = 0; e < 8; ++e) { const unsigned w = hw[e >> 1]; lw |= lo_encode(v[e], (e & 1) ? (w >> 16) : (w & 0xffffu)) << (4 * e); s2 += v[e] * v[e]; }
;                 *(GAS u32x4*)(HI + (size_t)row * DM + idx) = hw; __builtin_nontemporal_store(lw, (GAS unsigned*)(LO + (size_t)row * (DM / 2) + (idx >> 1))); } }
;         if (!LAST) { const float rn = __builtin_amdgcn_rsqf(wave_sum(s2) * (1.0f / DM) + RMS_EPS); if (lane == 0) *(GAS float*)(rs + row) = rn; } }
	v_and_b32_e32 v212, 0xffff0000, v91
	v_and_b32_sdwa v213, sext(v200), s57 dst_sel:DWORD dst_unused:UNUSED_PAD src0_sel:WORD_0 src1_sel:DWORD
	v_add_u32_e32 v221, v212, v213
	v_bfe_i32 v212, v200, 4, 16
	v_and_b32_e32 v212, 0xfffff000, v212
	v_bfe_i32 v213, v200, 8, 16
	v_lshl_add_u32 v222, v92, 16, v212
	v_and_b32_e32 v212, 0xffff0000, v92
	v_and_b32_e32 v213, 0xfffff000, v213
	v_add_u32_e32 v223, v212, v213
	v_bfe_i32 v212, v200, 12, 16
	v_and_b32_e32 v212, 0xfffff000, v212
	v_lshl_add_u32 v224, v93, 16, v212
	v_and_b32_e32 v212, 0xffff0000, v93
	v_and_b32_sdwa v213, sext(v200), s57 dst_sel:DWORD dst_unused:UNUSED_PAD src0_sel:WORD_1 src1_sel:DWORD
	v_add_u32_e32 v225, v212, v213
	v_lshlrev_b32_e32 v212, 16, v86
	v_mul_f32_e32 v212, v211, v212
	v_fmac_f32_e32 v218, v12, v212
	v_and_b32_e32 v212, 0xffff0000, v86
	v_mul_f32_e32 v212, v211, v212
	v_fmac_f32_e32 v219, v13, v212
	v_lshlrev_b32_e32 v212, 16, v87
	v_mul_f32_e32 v212, v211, v212
	v_fmac_f32_e32 v220, v14, v212
	v_and_b32_e32 v212, 0xffff0000, v87
	v_mul_f32_e32 v212, v211, v212
	v_fmac_f32_e32 v221, v15, v212
	v_lshlrev_b32_e32 v212, 16, v88
	v_mul_f32_e32 v212, v211, v212
	v_fmac_f32_e32 v222, v8, v212
	v_and_b32_e32 v212, 0xffff0000, v88
	v_mul_f32_e32 v212, v211, v212
	v_fmac_f32_e32 v223, v9, v212
	v_lshlrev_b32_e32 v212, 16, v89
	v_mul_f32_e32 v212, v211, v212
	v_fmac_f32_e32 v224, v10, v212
	v_and_b32_e32 v212, 0xffff0000, v89
	v_mul_f32_e32 v211, v211, v212
	v_fmac_f32_e32 v225, v11, v211
	v_cvt_pk_bf16_f32 v212, v218, v219
	v_fmac_f32_e32 v226, v218, v218
	v_lshlrev_b32_e32 v211, 16, v212
	v_sub_u32_e32 v211, v218, v211
	v_and_b32_e32 v218, 0xffff0000, v212
	v_cvt_pk_bf16_f32 v213, v220, v221
	v_sub_u32_e32 v218, v219, v218
	v_fmac_f32_e32 v226, v219, v219
	v_lshlrev_b32_e32 v219, 16, v213
	v_sub_u32_e32 v219, v220, v219
	v_fmac_f32_e32 v226, v220, v220
	v_and_b32_e32 v220, 0xffff0000, v213
	v_cvt_pk_bf16_f32 v214, v222, v223
	v_sub_u32_e32 v220, v221, v220
	v_fmac_f32_e32 v226, v221, v221
	v_lshlrev_b32_e32 v221, 16, v214
	v_sub_u32_e32 v221, v222, v221
	v_fmac_f32_e32 v226, v222, v222
	v_and_b32_e32 v222, 0xffff0000, v214
	v_cvt_pk_bf16_f32 v215, v224, v225
	v_sub_u32_e32 v222, v223, v222
	v_fmac_f32_e32 v226, v223, v223
	v_lshlrev_b32_e32 v223, 16, v215
	v_sub_u32_e32 v223, v224, v223
	v_fmac_f32_e32 v226, v224, v224
	v_and_b32_e32 v224, 0xffff0000, v215
	v_add_u32_e32 v211, 0x800, v211
	v_add_u32_e32 v218, 0x800, v218
	v_add_u32_e32 v219, 0x800, v219
	v_sub_u32_e32 v224, v225, v224
	v_ashrrev_i32_e32 v211, 12, v211
	v_ashrrev_i32_e32 v218, 12, v218
	v_ashrrev_i32_e32 v219, 12, v219
	v_add_u32_e32 v220, 0x800, v220
	v_add_u32_e32 v224, 0x800, v224
	v_min_i32_e32 v211, 7, v211
	v_min_i32_e32 v218, 7, v218
	v_min_i32_e32 v219, 7, v219
	v_ashrrev_i32_e32 v220, 12, v220
	v_add_u32_e32 v221, 0x800, v221
	v_add_u32_e32 v222, 0x800, v222
	v_ashrrev_i32_e32 v224, 12, v224
	v_and_b32_e32 v211, 15, v211
	v_lshlrev_b32_e32 v218, 4, v218
	v_lshlrev_b32_e32 v219, 8, v219
	v_min_i32_e32 v220, 7, v220
	v_ashrrev_i32_e32 v221, 12, v221
	v_ashrrev_i32_e32 v222, 12, v222
	v_add_u32_e32 v223, 0x800, v223
	v_min_i32_e32 v224, 7, v224
	v_and_b32_e32 v218, 0xf0, v218
	v_and_b32_e32 v219, 0xf00, v219
	v_lshlrev_b32_e32 v220, 12, v220
	v_min_i32_sdwa v221, v221, v192 dst_sel:WORD_1 dst_unused:UNUSED_PAD src0_sel:DWORD src1_sel:DWORD
	v_min_i32_e32 v222, 7, v222
	v_ashrrev_i32_e32 v223, 12, v223
	v_lshl_or_b32 v211, v224, 28, v211
	v_and_b32_e32 v220, 0xf000, v220
	v_and_b32_e32 v221, 0xf0000, v221
	v_lshlrev_b32_e32 v222, 20, v222
	v_min_i32_sdwa v223, v223, v192 dst_sel:BYTE_3 dst_unused:UNUSED_PAD src0_sel:DWORD src1_sel:DWORD
	v_or3_b32 v211, v211, v218, v219
	v_and_b32_e32 v222, 0xf00000, v222
	v_and_b32_e32 v223, 0xf000000, v223
	v_or3_b32 v211, v211, v220, v221
	v_or3_b32 v211, v211, v222, v223
	v_fmac_f32_e32 v226, v225, v225
	global_store_dwordx4 v[216:217], v[212:215], off offset:1024
	s_nop 1
	v_lshl_add_u64 v[212:213], s[44:45], 0, v[154:155]
	global_store_dword v[212:213], v211, off nt
	ds_bpermute_b32 v211, v184, v226
	s_waitcnt lgkmcnt(0)
	v_add_f32_e32 v211, v226, v211
	ds_bpermute_b32 v212, v185, v211
	s_waitcnt lgkmcnt(0)
	v_add_f32_e32 v211, v211, v212
	ds_bpermute_b32 v212, v195, v211
	s_waitcnt lgkmcnt(0)
	v_add_f32_e32 v211, v211, v212
	ds_bpermute_b32 v212, v196, v211
	s_waitcnt lgkmcnt(0)
	v_add_f32_e32 v211, v211, v212
	ds_bpermute_b32 v212, v197, v211
	s_waitcnt lgkmcnt(0)
	v_add_f32_e32 v211, v211, v212
	ds_bpermute_b32 v212, v198, v211
	s_and_saveexec_b64 s[44:45], s[40:41]
	s_cbranch_execz .LBB0_292
	s_waitcnt lgkmcnt(0)
	v_add_f32_e32 v211, v211, v212
	v_fmamk_f32 v211, v211, 0x3a800000, v188
	v_rsq_f32_e32 v211, v211
	s_lshl_b64 s[8:9], s[8:9], 2
	s_add_u32 s8, s66, s8
	s_addc_u32 s9, s67, s9
	global_store_dword v32, v211, s[8:9]
; __device__ __forceinline__ unsigned cvt_pk_bf16(float lo, float hi) { unsigned r; asm volatile("v_cvt_pk_bf16_f32 %0, %1, %2" : "=v"(r) : "v"(lo), "v"(hi)); return r; }
; #define GAS __attribute__((address_space(1)))
; __device__ __forceinline__ float bf_lo(unsigned w) { return __uint_as_float(w << 16); }
; template <bool HIN_F32, bool LAST>
; __device__ __forceinline__ void fin_compute(FinStage& S, float* out, bf16_t* HI, unsigned char* LO, float* rs, const f32x4 (&gpv)[4], float coef, int row0, int NGW, int lane) {
;     ...
;     for (int t = 0; t < 2; ++t) { const int row = row0 + t * NGW; float s2 = 0.f;
;         float tot = S.sp[t];
; #pragma unroll
;         for (int o = 1; o < 16; o <<= 1) tot += __shfl_xor(tot, o);
;         const float r = coef * __builtin_amdgcn_rsqf(tot * (1.0f / DM) + RMS_EPS);
; #pragma unroll
;         for (int j = 0; j < 2; ++j) { const int idx = 512 * j + 8 * lane; float v[8];
;             const u32x4 fw = S.fw[t][j];
;             if (HIN_F32) {
; #pragma unroll
;                 for (int e = 0; e < 8; ++e) v[e] = S.v[t][j][e >> 2][e & 3];
;             } else { const u32x4 hw = S.hw[t][j]; const unsigned lw = S.lw[t][j];
; #pragma unroll
;                 for (int e = 0; e < 8; ++e) { const unsigned w = hw[e >> 1]; v[e] = lo_decode((e & 1) ? (w >> 16) : (w & 0xffffu), (int)(lw << (28 - 4 * e)) >> 28); } }
; #pragma unroll
;             for (int e = 0; e < 8; ++e) { const unsigned w = fw[e >> 1]; v[e] += ((e & 1) ? bf_hi(w) : bf_lo(w)) * r * gpv[2 * j + (e >> 2)][e & 3]; }
;             if (LAST) { __builtin_nontemporal_store((f32x4){v[0], v[1], v[2], v[3]}, (GAS f32x4*)(out + (size_t)row * DM + idx)); __builtin_nontemporal_store((f32x4){v[4], v[5], v[6], v[7]}, (GAS f32x4*)(out + (size_t)row * DM + idx + 4)); }
;             else { u32x4 hw; hw.x = cvt_pk_bf16(v[0], v[1]); hw.y = cvt_pk_bf16(v[2], v[3]); hw.z = cvt_pk_bf16(v[4], v[5]); hw.w = cvt_pk_bf16(v[6], v[7]);
;                 unsigned lw = 0u;
; #pragma unroll
;                 for (int e = 0; e < 8; ++e) { const unsigned w = hw[e >> 1]; lw |= lo_encode(v[e], (e & 1) ? (w >> 16) : (w & 0xffffu)) << (4 * e); s2 += v[e] * v[e]; }
;                 *(GAS u32x4*)(HI + (size_t)row * DM + idx) = hw; __builtin_nontemporal_store(lw, (GAS unsigned*)(LO + (size_t)row * (DM / 2) + (idx >> 1))); } }
.LBB0_292:
	s_or_b64 exec, exec, s[44:45]
	ds_bpermute_b32 v211, v184, v210
	v_lshlrev_b32_e32 v213, 24, v201
	v_and_b32_sdwa v213, sext(v213), s57 dst_sel:DWORD dst_unused:UNUSED_PAD src0_sel:WORD_1 src1_sel:DWORD
	s_add_i32 s8, s85, s83
	s_ashr_i32 s9, s8, 31
	s_waitcnt lgkmcnt(0)
	v_add_f32_e32 v211, v210, v211
	ds_bpermute_b32 v212, v185, v211
	s_lshl_b64 s[46:47], s[8:9], 11
	s_lshl_b64 s[44:45], s[8:9], 9
	s_add_u32 s44, s0, s44
	s_addc_u32 s45, s50, s45
	s_waitcnt lgkmcnt(0)
	v_add_f32_e32 v211, v211, v212
	ds_bpermute_b32 v212, v195, v211
	s_waitcnt lgkmcnt(0)
	v_add_f32_e32 v211, v211, v212
	ds_bpermute_b32 v212, v196, v211
	s_waitcnt lgkmcnt(0)
	v_add_f32_e32 v211, v211, v212
	v_lshlrev_b32_e32 v212, 28, v201
	v_ashrrev_i32_e32 v212, 16, v212
	v_lshl_add_u32 v216, v106, 16, v212
	v_and_b32_e32 v212, 0xffff0000, v106
	v_add_u32_e32 v217, v212, v213
	v_lshlrev_b32_e32 v212, 20, v201
	v_and_b32_sdwa v212, sext(v212), s57 dst_sel:DWORD dst_unused:UNUSED_PAD src0_sel:WORD_1 src1_sel:DWORD
	v_lshl_add_u32 v218, v107, 16, v212
	v_and_b32_e32 v212, 0xffff0000, v107
	v_and_b32_sdwa v213, sext(v201), s57 dst_sel:DWORD dst_unused:UNUSED_PAD src0_sel:WORD_0 src1_sel:DWORD
	v_add_u32_e32 v219, v212, v213
	v_bfe_i32 v212, v201, 4, 16
	v_fmamk_f32 v211, v211, 0x3a800000, v188
	v_and_b32_e32 v212, 0xfffff000, v212
	v_bfe_i32 v213, v201, 8, 16
	v_rsq_f32_e32 v211, v211
	v_lshl_add_u32 v220, v108, 16, v212
	v_and_b32_e32 v212, 0xffff0000, v108
	v_and_b32_e32 v213, 0xfffff000, v213
	v_add_u32_e32 v221, v212, v213
	v_bfe_i32 v212, v201, 12, 16
	v_and_b32_e32 v212, 0xfffff000, v212
	v_lshl_add_u32 v222, v109, 16, v212
	v_and_b32_e32 v212, 0xffff0000, v109
	v_and_b32_sdwa v213, sext(v201), s57 dst_sel:DWORD dst_unused:UNUSED_PAD src0_sel:WORD_1 src1_sel:DWORD
	v_mul_f32_e32 v211, v33, v211
	v_add_u32_e32 v223, v212, v213
	v_lshlrev_b32_e32 v212, 16, v98
	v_mul_f32_e32 v212, v211, v212
	v_fmac_f32_e32 v216, v4, v212
	v_and_b32_e32 v212, 0xffff0000, v98
	v_mul_f32_e32 v212, v211, v212
	v_fmac_f32_e32 v217, v5, v212
	v_lshlrev_b32_e32 v212, 16, v99
	v_mul_f32_e32 v212, v211, v212
	v_fmac_f32_e32 v218, v6, v212
	v_and_b32_e32 v212, 0xffff0000, v99
	v_mul_f32_e32 v212, v211, v212
	v_fmac_f32_e32 v219, v7, v212
	v_lshlrev_b32_e32 v212, 16, v100
	v_mul_f32_e32 v212, v211, v212
	v_fmac_f32_e32 v220, v0, v212
	v_and_b32_e32 v212, 0xffff0000, v100
	v_mul_f32_e32 v212, v211, v212
	v_fmac_f32_e32 v221, v1, v212
	v_lshlrev_b32_e32 v212, 16, v101
	v_mul_f32_e32 v212, v211, v212
	v_fmac_f32_e32 v222, v2, v212
	v_and_b32_e32 v212, 0xffff0000, v101
	v_mul_f32_e32 v226, v217, v217
	v_mul_f32_e32 v212, v211, v212
	v_fmac_f32_e32 v226, v216, v216
	v_fmac_f32_e32 v223, v3, v212
	v_cvt_pk_bf16_f32 v212, v216, v217
	v_fmac_f32_e32 v226, v218, v218
	v_and_b32_e32 v225, 0xffff0000, v212
	v_cvt_pk_bf16_f32 v213, v218, v219
	v_lshlrev_b32_e32 v224, 16, v212
	v_sub_u32_e32 v225, v217, v225
	v_and_b32_e32 v217, 0xffff0000, v213
	v_fmac_f32_e32 v226, v219, v219
	v_cvt_pk_bf16_f32 v214, v220, v221
	v_sub_u32_e32 v224, v216, v224
	v_lshlrev_b32_e32 v216, 16, v213
	v_sub_u32_e32 v217, v219, v217
	v_fmac_f32_e32 v226, v220, v220
	v_and_b32_e32 v219, 0xffff0000, v214
	v_cvt_pk_bf16_f32 v215, v222, v223
	v_sub_u32_e32 v216, v218, v216
	v_sub_u32_e32 v219, v221, v219
	v_fmac_f32_e32 v226, v221, v221
	v_and_b32_e32 v221, 0xffff0000, v215
	v_add_u32_e32 v224, 0x800, v224
	v_add_u32_e32 v225, 0x800, v225
	v_add_u32_e32 v216, 0x800, v216
	v_lshlrev_b32_e32 v218, 16, v214
	v_sub_u32_e32 v221, v223, v221
	v_ashrrev_i32_e32 v224, 12, v224
	v_ashrrev_i32_e32 v225, 12, v225
	v_ashrrev_i32_e32 v216, 12, v216
	v_add_u32_e32 v217, 0x800, v217
	v_sub_u32_e32 v218, v220, v218
	v_lshlrev_b32_e32 v220, 16, v215
	v_add_u32_e32 v221, 0x800, v221
	v_min_i32_e32 v224, 7, v224
	v_min_i32_e32 v225, 7, v225
	v_min_i32_e32 v216, 7, v216
	v_ashrrev_i32_e32 v217, 12, v217
	v_add_u32_e32 v218, 0x800, v218
	v_add_u32_e32 v219, 0x800, v219
	v_sub_u32_e32 v220, v222, v220
	v_ashrrev_i32_e32 v221, 12, v221
	v_and_b32_e32 v224, 15, v224
	v_lshlrev_b32_e32 v225, 4, v225
	v_lshlrev_b32_e32 v216, 8, v216
	v_min_i32_e32 v217, 7, v217
	v_ashrrev_i32_e32 v218, 12, v218
	v_ashrrev_i32_e32 v219, 12, v219
	v_add_u32_e32 v220, 0x800, v220
	v_min_i32_e32 v221, 7, v221
	v_and_b32_e32 v225, 0xf0, v225
	v_and_b32_e32 v216, 0xf00, v216
	v_lshlrev_b32_e32 v217, 12, v217
	v_min_i32_sdwa v218, v218, v192 dst_sel:WORD_1 dst_unused:UNUSED_PAD src0_sel:DWORD src1_sel:DWORD
	v_min_i32_e32 v219, 7, v219
	v_ashrrev_i32_e32 v220, 12, v220
	v_lshl_or_b32 v221, v221, 28, v224
	v_and_b32_e32 v217, 0xf000, v217
	v_and_b32_e32 v218, 0xf0000, v218
	v_lshlrev_b32_e32 v219, 20, v219
	v_min_i32_sdwa v220, v220, v192 dst_sel:BYTE_3 dst_unused:UNUSED_PAD src0_sel:DWORD src1_sel:DWORD
	v_or3_b32 v216, v221, v225, v216
	v_and_b32_e32 v219, 0xf00000, v219
	v_and_b32_e32 v220, 0xf000000, v220
	v_or3_b32 v216, v216, v217, v218
	v_or3_b32 v218, v216, v219, v220
	v_lshl_add_u64 v[216:217], v[156:157], 0, s[46:47]
	global_store_dwordx4 v[216:217], v[212:215], off
	v_fmac_f32_e32 v226, v222, v222
	v_fmac_f32_e32 v226, v223, v223
	v_lshl_add_u64 v[212:213], s[44:45], 0, v[152:153]
	global_store_dword v[212:213], v218, off nt
	v_lshlrev_b32_e32 v212, 28, v203
	v_ashrrev_i32_e32 v212, 16, v212
; __device__ __forceinline__ unsigned cvt_pk_bf16(float lo, float hi) { unsigned r; asm volatile("v_cvt_pk_bf16_f32 %0, %1, %2" : "=v"(r) : "v"(lo), "v"(hi)); return r; }
; #define GAS __attribute__((address_space(1)))
; __device__ __forceinline__ float bf_lo(unsigned w) { return __uint_as_float(w << 16); }
; __device__ __forceinline__ float bf_hi(unsigned w) { return __uint_as_float(w & 0xffff0000u); }
; __device__ __forceinline__ float lo_decode(unsigned hi16, int q4) { return __uint_as_float((hi16 << 16) + (unsigned)(q4 << 12)); }
; template <bool HIN_F32, bool LAST>
; __device__ __forceinline__ void fin_compute(FinStage& S, float* out, bf16_t* HI, unsigned char* LO, float* rs, const f32x4 (&gpv)[4], float coef, int row0, int NGW, int lane) {
;     ...
;         for (int j = 0; j < 2; ++j) { const int idx = 512 * j + 8 * lane; float v[8];
;             const u32x4 fw = S.fw[t][j];
;             if (HIN_F32) {
; #pragma unroll
;                 for (int e = 0; e < 8; ++e) v[e] = S.v[t][j][e >> 2][e & 3];
;             } else { const u32x4 hw = S.hw[t][j]; const unsigned lw = S.lw[t][j];
; #pragma unroll
;                 for (int e = 0; e < 8; ++e) { const unsigned w = hw[e >> 1]; v[e] = lo_decode((e & 1) ? (w >> 16) : (w & 0xffffu), (int)(lw << (28 - 4 * e)) >> 28); } }
; #pragma unroll
;             for (int e = 0; e < 8; ++e) { const unsigned w = fw[e >> 1]; v[e] += ((e & 1) ? bf_hi(w) : bf_lo(w)) * r * gpv[2 * j + (e >> 2)][e & 3]; }
;             if (LAST) { __builtin_nontemporal_store((f32x4){v[0], v[1], v[2], v[3]}, (GAS f32x4*)(out + (size_t)row * DM + idx)); __builtin_nontemporal_store((f32x4){v[4], v[5], v[6], v[7]}, (GAS f32x4*)(out + (size_t)row * DM + idx + 4)); }
;             else { u32x4 hw; hw.x = cvt_pk_bf16(v[0], v[1]); hw.y = cvt_pk_bf16(v[2], v[3]); hw.z = cvt_pk_bf16(v[4], v[5]); hw.w = cvt_pk_bf16(v[6], v[7]);
;                 unsigned lw = 0u;
; #pragma unroll
;                 for (int e = 0; e < 8; ++e) { const unsigned w = hw[e >> 1]; lw |= lo_encode(v[e], (e & 1) ? (w >> 16) : (w & 0xffffu)) << (4 * e); s2 += v[e] * v[e]; }
;                 *(GAS u32x4*)(HI + (size_t)row * DM + idx) = hw; __builtin_nontemporal_store(lw, (GAS unsigned*)(LO + (size_t)row * (DM / 2) + (idx >> 1))); } }
;         if (!LAST) { const float rn = __builtin_amdgcn_rsqf(wave_sum(s2) * (1.0f / DM) + RMS_EPS); if (lane == 0) *(GAS float*)(rs + row) = rn; } }
	v_lshlrev_b32_e32 v213, 24, v203
	v_lshl_add_u32 v218, v102, 16, v212
	v_and_b32_e32 v212, 0xffff0000, v102
	v_and_b32_sdwa v213, sext(v213), s57 dst_sel:DWORD dst_unused:UNUSED_PAD src0_sel:WORD_1 src1_sel:DWORD
	v_add_u32_e32 v219, v212, v213
	v_lshlrev_b32_e32 v212, 20, v203
	v_and_b32_sdwa v212, sext(v212), s57 dst_sel:DWORD dst_unused:UNUSED_PAD src0_sel:WORD_1 src1_sel:DWORD
	v_lshl_add_u32 v220, v103, 16, v212
	v_and_b32_e32 v212, 0xffff0000, v103
	v_and_b32_sdwa v213, sext(v203), s57 dst_sel:DWORD dst_unused:UNUSED_PAD src0_sel:WORD_0 src1_sel:DWORD
	v_add_u32_e32 v221, v212, v213
	v_bfe_i32 v212, v203, 4, 16
	v_and_b32_e32 v212, 0xfffff000, v212
	v_bfe_i32 v213, v203, 8, 16
	v_lshl_add_u32 v222, v104, 16, v212
	v_and_b32_e32 v212, 0xffff0000, v104
	v_and_b32_e32 v213, 0xfffff000, v213
	v_add_u32_e32 v223, v212, v213
	v_bfe_i32 v212, v203, 12, 16
	v_and_b32_e32 v212, 0xfffff000, v212
	v_lshl_add_u32 v224, v105, 16, v212
	v_and_b32_e32 v212, 0xffff0000, v105
	v_and_b32_sdwa v213, sext(v203), s57 dst_sel:DWORD dst_unused:UNUSED_PAD src0_sel:WORD_1 src1_sel:DWORD
	v_add_u32_e32 v225, v212, v213
	v_lshlrev_b32_e32 v212, 16, v122
	v_mul_f32_e32 v212, v211, v212
	v_fmac_f32_e32 v218, v12, v212
	v_and_b32_e32 v212, 0xffff0000, v122
	v_mul_f32_e32 v212, v211, v212
	v_fmac_f32_e32 v219, v13, v212
	v_lshlrev_b32_e32 v212, 16, v123
	v_mul_f32_e32 v212, v211, v212
	v_fmac_f32_e32 v220, v14, v212
	v_and_b32_e32 v212, 0xffff0000, v123
	v_mul_f32_e32 v212, v211, v212
	v_fmac_f32_e32 v221, v15, v212
	v_lshlrev_b32_e32 v212, 16, v124
	v_mul_f32_e32 v212, v211, v212
	v_fmac_f32_e32 v222, v8, v212
	v_and_b32_e32 v212, 0xffff0000, v124
	v_mul_f32_e32 v212, v211, v212
	v_fmac_f32_e32 v223, v9, v212
	v_lshlrev_b32_e32 v212, 16, v125
	v_mul_f32_e32 v212, v211, v212
	v_fmac_f32_e32 v224, v10, v212
	v_and_b32_e32 v212, 0xffff0000, v125
	v_mul_f32_e32 v211, v211, v212
	v_fmac_f32_e32 v225, v11, v211
	v_cvt_pk_bf16_f32 v212, v218, v219
	v_fmac_f32_e32 v226, v218, v218
	v_lshlrev_b32_e32 v211, 16, v212
	v_sub_u32_e32 v211, v218, v211
	v_and_b32_e32 v218, 0xffff0000, v212
	v_cvt_pk_bf16_f32 v213, v220, v221
	v_sub_u32_e32 v218, v219, v218
	v_fmac_f32_e32 v226, v219, v219
	v_lshlrev_b32_e32 v219, 16, v213
	v_sub_u32_e32 v219, v220, v219
	v_fmac_f32_e32 v226, v220, v220
	v_and_b32_e32 v220, 0xffff0000, v213
	v_cvt_pk_bf16_f32 v214, v222, v223
	v_sub_u32_e32 v220, v221, v220
	v_fmac_f32_e32 v226, v221, v221
	v_lshlrev_b32_e32 v221, 16, v214
	v_sub_u32_e32 v221, v222, v221
	v_fmac_f32_e32 v226, v222, v222
	v_and_b32_e32 v222, 0xffff0000, v214
	v_cvt_pk_bf16_f32 v215, v224, v225
	v_sub_u32_e32 v222, v223, v222
	v_fmac_f32_e32 v226, v223, v223
	v_lshlrev_b32_e32 v223, 16, v215
	v_sub_u32_e32 v223, v224, v223
	v_fmac_f32_e32 v226, v224, v224
	v_and_b32_e32 v224, 0xffff0000, v215
	v_add_u32_e32 v211, 0x800, v211
	v_add_u32_e32 v218, 0x800, v218
	v_add_u32_e32 v219, 0x800, v219
	v_sub_u32_e32 v224, v225, v224
	v_ashrrev_i32_e32 v211, 12, v211
	v_ashrrev_i32_e32 v218, 12, v218
	v_ashrrev_i32_e32 v219, 12, v219
	v_add_u32_e32 v220, 0x800, v220
	v_add_u32_e32 v224, 0x800, v224
	v_min_i32_e32 v211, 7, v211
	v_min_i32_e32 v218, 7, v218
	v_min_i32_e32 v219, 7, v219
	v_ashrrev_i32_e32 v220, 12, v220
	v_add_u32_e32 v221, 0x800, v221
	v_add_u32_e32 v222, 0x800, v222
	v_ashrrev_i32_e32 v224, 12, v224
	v_and_b32_e32 v211, 15, v211
	v_lshlrev_b32_e32 v218, 4, v218
	v_lshlrev_b32_e32 v219, 8, v219
	v_min_i32_e32 v220, 7, v220
	v_ashrrev_i32_e32 v221, 12, v221
	v_ashrrev_i32_e32 v222, 12, v222
	v_add_u32_e32 v223, 0x800, v223
	v_min_i32_e32 v224, 7, v224
	v_and_b32_e32 v218, 0xf0, v218
	v_and_b32_e32 v219, 0xf00, v219
	v_lshlrev_b32_e32 v220, 12, v220
	v_min_i32_sdwa v221, v221, v192 dst_sel:WORD_1 dst_unused:UNUSED_PAD src0_sel:DWORD src1_sel:DWORD
	v_min_i32_e32 v222, 7, v222
	v_ashrrev_i32_e32 v223, 12, v223
	v_lshl_or_b32 v211, v224, 28, v211
	v_and_b32_e32 v220, 0xf000, v220
	v_and_b32_e32 v221, 0xf0000, v221
	v_lshlrev_b32_e32 v222, 20, v222
	v_min_i32_sdwa v223, v223, v192 dst_sel:BYTE_3 dst_unused:UNUSED_PAD src0_sel:DWORD src1_sel:DWORD
	v_or3_b32 v211, v211, v218, v219
	v_and_b32_e32 v222, 0xf00000, v222
	v_and_b32_e32 v223, 0xf000000, v223
	v_or3_b32 v211, v211, v220, v221
	v_or3_b32 v211, v211, v222, v223
	v_fmac_f32_e32 v226, v225, v225
	global_store_dwordx4 v[216:217], v[212:215], off offset:1024
	s_nop 1
	v_lshl_add_u64 v[212:213], s[44:45], 0, v[154:155]
	global_store_dword v[212:213], v211, off nt
	ds_bpermute_b32 v211, v184, v226
	s_waitcnt lgkmcnt(0)
	v_add_f32_e32 v211, v226, v211
	ds_bpermute_b32 v212, v185, v211
	s_waitcnt lgkmcnt(0)
	v_add_f32_e32 v211, v211, v212
	ds_bpermute_b32 v212, v195, v211
	s_waitcnt lgkmcnt(0)
	v_add_f32_e32 v211, v211, v212
	ds_bpermute_b32 v212, v196, v211
	s_waitcnt lgkmcnt(0)
	v_add_f32_e32 v211, v211, v212
	ds_bpermute_b32 v212, v197, v211
	s_waitcnt lgkmcnt(0)
	v_add_f32_e32 v211, v211, v212
	ds_bpermute_b32 v212, v198, v211
	s_and_saveexec_b64 s[44:45], s[40:41]
	s_cbranch_execz .LBB0_271
	s_waitcnt lgkmcnt(0)
	v_add_f32_e32 v211, v211, v212
	v_fmamk_f32 v211, v211, 0x3a800000, v188
	v_rsq_f32_e32 v211, v211
	s_lshl_b64 s[8:9], s[8:9], 2
	s_add_u32 s8, s66, s8
	s_addc_u32 s9, s67, s9
	global_store_dword v32, v211, s[8:9]
	s_branch .LBB0_271

; __global__ void __launch_bounds__(NTHREADS, 2) fwd_kernel(Args a) {
	.amdhsa_kernel _Z10fwd_kernel4Args
		.amdhsa_group_segment_fixed_size 0
		.amdhsa_private_segment_fixed_size 0
		.amdhsa_kernarg_size 384
		.amdhsa_user_sgpr_count 2
		.amdhsa_user_sgpr_dispatch_ptr 0
		.amdhsa_user_sgpr_queue_ptr 0
		.amdhsa_user_sgpr_kernarg_segment_ptr 1
		.amdhsa_user_sgpr_dispatch_id 0
		.amdhsa_user_sgpr_kernarg_preload_length 0
		.amdhsa_user_sgpr_kernarg_preload_offset 0
		.amdhsa_user_sgpr_private_segment_size 0
		.amdhsa_uses_dynamic_stack 0
		.amdhsa_enable_private_segment 0
		.amdhsa_system_sgpr_workgroup_id_x 1
		.amdhsa_system_sgpr_workgroup_id_y 0
		.amdhsa_system_sgpr_workgroup_id_z 0
		.amdhsa_system_sgpr_workgroup_info 0
		.amdhsa_system_vgpr_workitem_id 2
		.amdhsa_next_free_vgpr 256
		.amdhsa_next_free_sgpr 102
		.amdhsa_accum_offset 256
		.amdhsa_reserve_vcc 1
		.amdhsa_float_round_mode_32 0
		.amdhsa_float_round_mode_16_64 0
		.amdhsa_float_denorm_mode_32 3
		.amdhsa_float_denorm_mode_16_64 3
		.amdhsa_dx10_clamp 1
		.amdhsa_ieee_mode 1
		.amdhsa_fp16_overflow 0
		.amdhsa_tg_split 0
		.amdhsa_exception_fp_ieee_invalid_op 0
		.amdhsa_exception_fp_denorm_src 0
		.amdhsa_exception_fp_ieee_div_zero 0
		.amdhsa_exception_fp_ieee_overflow 0
		.amdhsa_exception_fp_ieee_underflow 0
		.amdhsa_exception_fp_ieee_inexact 0
		.amdhsa_exception_int_div_zero 0
	.end_amdhsa_kernel

; __global__ void __launch_bounds__(NTHREADS, 2) fwd_kernel(Args a) {
amdhsa.kernels:
  - .agpr_count:     0
    .args:
      - .offset:         0
        .size:           128
        .value_kind:     by_value
      - .offset:         128
        .size:           4
        .value_kind:     hidden_block_count_x
      - .offset:         132
        .size:           4
        .value_kind:     hidden_block_count_y
      - .offset:         136
        .size:           4
        .value_kind:     hidden_block_count_z
      - .offset:         140
        .size:           2
        .value_kind:     hidden_group_size_x
      - .offset:         142
        .size:           2
        .value_kind:     hidden_group_size_y
      - .offset:         144
        .size:           2
        .value_kind:     hidden_group_size_z
      - .offset:         146
        .size:           2
        .value_kind:     hidden_remainder_x
      - .offset:         148
        .size:           2
        .value_kind:     hidden_remainder_y
      - .offset:         150
        .size:           2
        .value_kind:     hidden_remainder_z
      - .offset:         168
        .size:           8
        .value_kind:     hidden_global_offset_x
      - .offset:         176
        .size:           8
        .value_kind:     hidden_global_offset_y
      - .offset:         184
        .size:           8
        .value_kind:     hidden_global_offset_z
      - .offset:         192
        .size:           2
        .value_kind:     hidden_grid_dims
      - .offset:         216
        .size:           8
        .value_kind:     hidden_multigrid_sync_arg
      - .offset:         248
        .size:           4
        .value_kind:     hidden_dynamic_lds_size
    .group_segment_fixed_size: 0
    .kernarg_segment_align: 8
    .kernarg_segment_size: 384
    .language:       OpenCL C
    .language_version:
      - 2
      - 0
    .max_flat_workgroup_size: 512
    .name:           _Z10fwd_kernel4Args
    .private_segment_fixed_size: 0
    .sgpr_count:     108
    .sgpr_spill_count: 262
    .symbol:         _Z10fwd_kernel4Args.kd
    .uniform_work_group_size: 1
    .uses_dynamic_stack: false
    .vgpr_count:     256
    .vgpr_spill_count: 0
    .wavefront_size: 64
